# P9 layer-0 FFN-down epilogue fused with the following LayerNorm (old phase 10): U also kept in registers, per-row partial (mean,M2) exchange among the 4 column-tile workgroups, bf16 rows + (mean,rstd)
# speedup vs baseline: 1.0813x; 1.0018x over previous
.LBB0_1460:
	v_lshlrev_b32_e32 v130, 3, v153
	v_and_b32_e32 v190, 0x78, v130
	v_ashrrev_i32_e32 v152, 4, v153
	v_lshrrev_b32_e32 v130, 1, v153
	v_and_b32_e32 v191, 0x60, v130
	v_or_b32_e32 v130, 4, v190
	v_lshlrev_b32_e32 v132, 2, v152
	v_bitop3_b32 v133, v132, v190, 48 bitop3:0x6c
	v_bitop3_b32 v132, v132, v130, 48 bitop3:0x6c
	v_lshlrev_b32_e32 v134, 9, v152
	v_lshlrev_b32_e32 v132, 2, v132
	v_add_u32_e32 v151, 32, v152
	v_lshlrev_b32_e32 v133, 2, v133
	v_add3_u32 v148, s64, v132, v134
	v_lshlrev_b32_e32 v132, 2, v151
	v_add3_u32 v147, s64, v133, v134
	v_bitop3_b32 v133, v132, v190, 48 bitop3:0x6c
	v_bitop3_b32 v132, v132, v130, 48 bitop3:0x6c
	v_lshlrev_b32_e32 v134, 9, v151
	v_lshlrev_b32_e32 v132, 2, v132
	v_add_u32_e32 v150, 64, v152
	v_lshlrev_b32_e32 v133, 2, v133
	v_add3_u32 v145, s64, v132, v134
	v_lshlrev_b32_e32 v132, 2, v150
	v_add3_u32 v146, s64, v133, v134
	v_bitop3_b32 v133, v132, v190, 48 bitop3:0x6c
	v_bitop3_b32 v132, v132, v130, 48 bitop3:0x6c
	v_lshlrev_b32_e32 v134, 9, v150
	v_lshlrev_b32_e32 v132, 2, v132
	v_add_u32_e32 v149, 0x60, v152
	v_lshlrev_b32_e32 v133, 2, v133
	v_add3_u32 v143, s64, v132, v134
	v_lshlrev_b32_e32 v132, 2, v149
	v_add3_u32 v144, s64, v133, v134
	v_bitop3_b32 v133, v132, v190, 48 bitop3:0x6c
	v_bitop3_b32 v130, v132, v130, 48 bitop3:0x6c
	v_lshlrev_b32_e32 v133, 2, v133
	v_lshlrev_b32_e32 v134, 9, v149
	v_lshlrev_b32_e32 v130, 2, v130
	s_lshl_b64 s[50:51], s[46:47], 2
	v_add3_u32 v141, s64, v133, v134
	v_add3_u32 v140, s64, v130, v134
	v_bfe_u32 v189, v153, 4, 2
	v_and_b32_e32 v188, 15, v153
	v_lshlrev_b32_e32 v193, 4, v189
	v_lshlrev_b32_e32 v153, 7, v153
	v_or_b32_e32 v192, v191, v188
	v_bitop3_b32 v188, v191, v193, v188 bitop3:0x36
	v_and_b32_e32 v153, 0xffff8000, v153
	v_lshlrev_b32_e32 v188, 2, v188
	v_lshl_or_b32 v189, v189, 11, v153
	v_add3_u32 v153, s64, v188, v189
	v_bitop3_b32 v149, v192, v193, 16 bitop3:0x36
	v_lshlrev_b32_e32 v149, 2, v149
	v_add3_u32 v149, s64, v149, v189
	v_lshrrev_b32_e32 v227, 4, v0
	v_add_u32_e32 v130, s73, v227
	v_lshlrev_b32_e32 v227, 3, v227
	v_and_b32_e32 v226, 15, v0
	v_lshlrev_b32_e32 v226, 5, v226
	s_lshl_b32 s0, s46, 2
	v_add_u32_e32 v226, s0, v226
	v_mov_b32_e32 v229, 0
	v_mov_b32_e32 v228, v130
	v_lshlrev_b64 v[228:229], 12, v[228:229]
	v_mov_b32_e32 v230, v226
	v_mov_b32_e32 v231, 0
	v_lshl_add_u64 v[228:229], v[228:229], 0, v[230:231]
	v_lshl_add_u64 v[230:231], s[66:67], 0, v[228:229]
	s_lshl_b32 s0, s73, 3
	s_add_u32 s52, s62, 0xf000000
	s_addc_u32 s53, s63, 0
	s_add_u32 s52, s52, s0
	s_addc_u32 s53, s53, 0
	v_readlane_b32 s70, v253, 8
	v_readlane_b32 s71, v253, 9
	v_readlane_b32 s74, v253, 10
	v_readlane_b32 s75, v253, 11
	s_mov_b32 s36, 0x20000
	s_mov_b32 s37, 0
	s_mov_b32 s39, 0
	s_nop 1
	s_mov_b32 s38, 0x0
	v_lshl_add_u64 v[150:151], v[230:231], 0, s[38:39]
	v_lshl_add_u64 v[220:221], v[150:151], 0, s[36:37]
	v_lshl_add_u64 v[222:223], v[220:221], 0, s[36:37]
	v_lshl_add_u64 v[224:225], v[222:223], 0, s[36:37]
	global_load_dwordx2 v[246:247], v227, s[52:53] offset:0
	global_load_dwordx2 v[248:249], v227, s[52:53] offset:256
	global_load_dwordx2 v[250:251], v227, s[52:53] offset:512
	global_load_dwordx2 v[218:219], v227, s[52:53] offset:768
	global_load_dwordx4 v[132:135], v226, s[70:71] offset:0
	global_load_dwordx4 v[136:139], v226, s[70:71] offset:16
	global_load_dwordx4 v[238:241], v226, s[74:75] offset:0
	global_load_dwordx4 v[242:245], v226, s[74:75] offset:16
	global_load_dwordx4 v[186:189], v[150:151], off
	global_load_dwordx4 v[190:193], v[150:151], off offset:16
	global_load_dwordx4 v[194:197], v[220:221], off
	global_load_dwordx4 v[198:201], v[220:221], off offset:16
	global_load_dwordx4 v[202:205], v[222:223], off
	global_load_dwordx4 v[206:209], v[222:223], off offset:16
	global_load_dwordx4 v[210:213], v[224:225], off
	global_load_dwordx4 v[214:217], v[224:225], off offset:16
	ds_write2st64_b32 v153, v126, v127 offset1:2
	ds_write2st64_b32 v153, v128, v129 offset0:4 offset1:6
	ds_write2st64_b32 v149, v98, v99 offset1:2
	ds_write2st64_b32 v149, v100, v101 offset0:4 offset1:6
	ds_write2st64_b32 v153, v102, v103 offset0:32 offset1:34
	ds_write2st64_b32 v153, v104, v105 offset0:36 offset1:38
	ds_write2st64_b32 v149, v106, v107 offset0:32 offset1:34
	ds_write2st64_b32 v149, v108, v109 offset0:36 offset1:38
	ds_write2st64_b32 v153, v110, v111 offset0:64 offset1:66
	ds_write2st64_b32 v153, v112, v113 offset0:68 offset1:70
	ds_write2st64_b32 v149, v114, v115 offset0:64 offset1:66
	ds_write2st64_b32 v149, v116, v117 offset0:68 offset1:70
	ds_write2st64_b32 v153, v118, v119 offset0:96 offset1:98
	ds_write2st64_b32 v153, v120, v121 offset0:100 offset1:102
	ds_write2st64_b32 v149, v122, v123 offset0:96 offset1:98
	ds_write2st64_b32 v149, v124, v125 offset0:100 offset1:102
	s_waitcnt lgkmcnt(0)
	s_barrier
	ds_read_b128 v[154:157], v147
	ds_read_b128 v[158:161], v148
	ds_read_b128 v[162:165], v146
	ds_read_b128 v[166:169], v145
	ds_read_b128 v[170:173], v144
	ds_read_b128 v[174:177], v143
	ds_read_b128 v[178:181], v141
	ds_read_b128 v[182:185], v140
	s_waitcnt vmcnt(0) lgkmcnt(0)
	s_barrier
	v_pk_add_f32 v[186:187], v[186:187], v[246:247] op_sel_hi:[1,0] neg_lo:[0,1] neg_hi:[0,1]
	v_pk_mul_f32 v[186:187], v[186:187], v[246:247] op_sel:[0,1]
	v_pk_fma_f32 v[186:187], v[132:133], v[186:187], v[238:239]
	v_pk_fma_f32 v[98:99], v[186:187], s[42:43], v[154:155] op_sel_hi:[1,0,1]
	v_pk_add_f32 v[188:189], v[188:189], v[246:247] op_sel_hi:[1,0] neg_lo:[0,1] neg_hi:[0,1]
	v_pk_mul_f32 v[188:189], v[188:189], v[246:247] op_sel:[0,1]
	v_pk_fma_f32 v[188:189], v[134:135], v[188:189], v[240:241]
	v_pk_fma_f32 v[100:101], v[188:189], s[42:43], v[156:157] op_sel_hi:[1,0,1]
	v_pk_add_f32 v[190:191], v[190:191], v[246:247] op_sel_hi:[1,0] neg_lo:[0,1] neg_hi:[0,1]
	v_pk_mul_f32 v[190:191], v[190:191], v[246:247] op_sel:[0,1]
	v_pk_fma_f32 v[190:191], v[136:137], v[190:191], v[242:243]
	v_pk_fma_f32 v[102:103], v[190:191], s[42:43], v[158:159] op_sel_hi:[1,0,1]
	v_pk_add_f32 v[192:193], v[192:193], v[246:247] op_sel_hi:[1,0] neg_lo:[0,1] neg_hi:[0,1]
	v_pk_mul_f32 v[192:193], v[192:193], v[246:247] op_sel:[0,1]
	v_pk_fma_f32 v[192:193], v[138:139], v[192:193], v[244:245]
	v_pk_fma_f32 v[104:105], v[192:193], s[42:43], v[160:161] op_sel_hi:[1,0,1]
	global_store_dwordx4 v[150:151], v[98:101], off
	global_store_dwordx4 v[150:151], v[102:105], off offset:16
	v_pk_add_f32 v[194:195], v[194:195], v[248:249] op_sel_hi:[1,0] neg_lo:[0,1] neg_hi:[0,1]
	v_pk_mul_f32 v[194:195], v[194:195], v[248:249] op_sel:[0,1]
	v_pk_fma_f32 v[194:195], v[132:133], v[194:195], v[238:239]
	v_pk_fma_f32 v[106:107], v[194:195], s[42:43], v[162:163] op_sel_hi:[1,0,1]
	v_pk_add_f32 v[196:197], v[196:197], v[248:249] op_sel_hi:[1,0] neg_lo:[0,1] neg_hi:[0,1]
	v_pk_mul_f32 v[196:197], v[196:197], v[248:249] op_sel:[0,1]
	v_pk_fma_f32 v[196:197], v[134:135], v[196:197], v[240:241]
	v_pk_fma_f32 v[108:109], v[196:197], s[42:43], v[164:165] op_sel_hi:[1,0,1]
	v_pk_add_f32 v[198:199], v[198:199], v[248:249] op_sel_hi:[1,0] neg_lo:[0,1] neg_hi:[0,1]
	v_pk_mul_f32 v[198:199], v[198:199], v[248:249] op_sel:[0,1]
	v_pk_fma_f32 v[198:199], v[136:137], v[198:199], v[242:243]
	v_pk_fma_f32 v[110:111], v[198:199], s[42:43], v[166:167] op_sel_hi:[1,0,1]
	v_pk_add_f32 v[200:201], v[200:201], v[248:249] op_sel_hi:[1,0] neg_lo:[0,1] neg_hi:[0,1]
	v_pk_mul_f32 v[200:201], v[200:201], v[248:249] op_sel:[0,1]
	v_pk_fma_f32 v[200:201], v[138:139], v[200:201], v[244:245]
	v_pk_fma_f32 v[112:113], v[200:201], s[42:43], v[168:169] op_sel_hi:[1,0,1]
	global_store_dwordx4 v[220:221], v[106:109], off
	global_store_dwordx4 v[220:221], v[110:113], off offset:16
	v_pk_add_f32 v[202:203], v[202:203], v[250:251] op_sel_hi:[1,0] neg_lo:[0,1] neg_hi:[0,1]
	v_pk_mul_f32 v[202:203], v[202:203], v[250:251] op_sel:[0,1]
	v_pk_fma_f32 v[202:203], v[132:133], v[202:203], v[238:239]
	v_pk_fma_f32 v[114:115], v[202:203], s[42:43], v[170:171] op_sel_hi:[1,0,1]
	v_pk_add_f32 v[204:205], v[204:205], v[250:251] op_sel_hi:[1,0] neg_lo:[0,1] neg_hi:[0,1]
	v_pk_mul_f32 v[204:205], v[204:205], v[250:251] op_sel:[0,1]
	v_pk_fma_f32 v[204:205], v[134:135], v[204:205], v[240:241]
	v_pk_fma_f32 v[116:117], v[204:205], s[42:43], v[172:173] op_sel_hi:[1,0,1]
	v_pk_add_f32 v[206:207], v[206:207], v[250:251] op_sel_hi:[1,0] neg_lo:[0,1] neg_hi:[0,1]
	v_pk_mul_f32 v[206:207], v[206:207], v[250:251] op_sel:[0,1]
	v_pk_fma_f32 v[206:207], v[136:137], v[206:207], v[242:243]
	v_pk_fma_f32 v[118:119], v[206:207], s[42:43], v[174:175] op_sel_hi:[1,0,1]
	v_pk_add_f32 v[208:209], v[208:209], v[250:251] op_sel_hi:[1,0] neg_lo:[0,1] neg_hi:[0,1]
	v_pk_mul_f32 v[208:209], v[208:209], v[250:251] op_sel:[0,1]
	v_pk_fma_f32 v[208:209], v[138:139], v[208:209], v[244:245]
	v_pk_fma_f32 v[120:121], v[208:209], s[42:43], v[176:177] op_sel_hi:[1,0,1]
	global_store_dwordx4 v[222:223], v[114:117], off
	global_store_dwordx4 v[222:223], v[118:121], off offset:16
	v_pk_add_f32 v[210:211], v[210:211], v[218:219] op_sel_hi:[1,0] neg_lo:[0,1] neg_hi:[0,1]
	v_pk_mul_f32 v[210:211], v[210:211], v[218:219] op_sel:[0,1]
	v_pk_fma_f32 v[210:211], v[132:133], v[210:211], v[238:239]
	v_pk_fma_f32 v[122:123], v[210:211], s[42:43], v[178:179] op_sel_hi:[1,0,1]
	v_pk_add_f32 v[212:213], v[212:213], v[218:219] op_sel_hi:[1,0] neg_lo:[0,1] neg_hi:[0,1]
	v_pk_mul_f32 v[212:213], v[212:213], v[218:219] op_sel:[0,1]
	v_pk_fma_f32 v[212:213], v[134:135], v[212:213], v[240:241]
	v_pk_fma_f32 v[124:125], v[212:213], s[42:43], v[180:181] op_sel_hi:[1,0,1]
	v_pk_add_f32 v[214:215], v[214:215], v[218:219] op_sel_hi:[1,0] neg_lo:[0,1] neg_hi:[0,1]
	v_pk_mul_f32 v[214:215], v[214:215], v[218:219] op_sel:[0,1]
	v_pk_fma_f32 v[214:215], v[136:137], v[214:215], v[242:243]
	v_pk_fma_f32 v[126:127], v[214:215], s[42:43], v[182:183] op_sel_hi:[1,0,1]
	v_pk_add_f32 v[216:217], v[216:217], v[218:219] op_sel_hi:[1,0] neg_lo:[0,1] neg_hi:[0,1]
	v_pk_mul_f32 v[216:217], v[216:217], v[218:219] op_sel:[0,1]
	v_pk_fma_f32 v[216:217], v[138:139], v[216:217], v[244:245]
	v_pk_fma_f32 v[128:129], v[216:217], s[42:43], v[184:185] op_sel_hi:[1,0,1]
	global_store_dwordx4 v[224:225], v[122:125], off
	global_store_dwordx4 v[224:225], v[126:129], off offset:16
	s_mov_b32 s38, 0x200
	v_lshl_add_u64 v[150:151], v[230:231], 0, s[38:39]
	v_lshl_add_u64 v[220:221], v[150:151], 0, s[36:37]
	v_lshl_add_u64 v[222:223], v[220:221], 0, s[36:37]
	v_lshl_add_u64 v[224:225], v[222:223], 0, s[36:37]
	global_load_dwordx2 v[246:247], v227, s[52:53] offset:0
	global_load_dwordx2 v[248:249], v227, s[52:53] offset:256
	global_load_dwordx2 v[250:251], v227, s[52:53] offset:512
	global_load_dwordx2 v[218:219], v227, s[52:53] offset:768
	global_load_dwordx4 v[132:135], v226, s[70:71] offset:512
	global_load_dwordx4 v[136:139], v226, s[70:71] offset:528
	global_load_dwordx4 v[238:241], v226, s[74:75] offset:512
	global_load_dwordx4 v[242:245], v226, s[74:75] offset:528
	global_load_dwordx4 v[186:189], v[150:151], off
	global_load_dwordx4 v[190:193], v[150:151], off offset:16
	global_load_dwordx4 v[194:197], v[220:221], off
	global_load_dwordx4 v[198:201], v[220:221], off offset:16
	global_load_dwordx4 v[202:205], v[222:223], off
	global_load_dwordx4 v[206:209], v[222:223], off offset:16
	global_load_dwordx4 v[210:213], v[224:225], off
	global_load_dwordx4 v[214:217], v[224:225], off offset:16
	ds_write2st64_b32 v153, v66, v67 offset1:2
	ds_write2st64_b32 v153, v68, v69 offset0:4 offset1:6
	ds_write2st64_b32 v149, v70, v71 offset1:2
	ds_write2st64_b32 v149, v72, v73 offset0:4 offset1:6
	ds_write2st64_b32 v153, v74, v75 offset0:32 offset1:34
	ds_write2st64_b32 v153, v76, v77 offset0:36 offset1:38
	ds_write2st64_b32 v149, v78, v79 offset0:32 offset1:34
	ds_write2st64_b32 v149, v80, v81 offset0:36 offset1:38
	ds_write2st64_b32 v153, v82, v83 offset0:64 offset1:66
	ds_write2st64_b32 v153, v84, v85 offset0:68 offset1:70
	ds_write2st64_b32 v149, v86, v87 offset0:64 offset1:66
	ds_write2st64_b32 v149, v88, v89 offset0:68 offset1:70
	ds_write2st64_b32 v153, v90, v91 offset0:96 offset1:98
	ds_write2st64_b32 v153, v92, v93 offset0:100 offset1:102
	ds_write2st64_b32 v149, v94, v95 offset0:96 offset1:98
	ds_write2st64_b32 v149, v96, v97 offset0:100 offset1:102
	s_waitcnt lgkmcnt(0)
	s_barrier
	ds_read_b128 v[154:157], v147
	ds_read_b128 v[158:161], v148
	ds_read_b128 v[162:165], v146
	ds_read_b128 v[166:169], v145
	ds_read_b128 v[170:173], v144
	ds_read_b128 v[174:177], v143
	ds_read_b128 v[178:181], v141
	ds_read_b128 v[182:185], v140
	s_waitcnt vmcnt(0) lgkmcnt(0)
	s_barrier
	v_pk_add_f32 v[186:187], v[186:187], v[246:247] op_sel_hi:[1,0] neg_lo:[0,1] neg_hi:[0,1]
	v_pk_mul_f32 v[186:187], v[186:187], v[246:247] op_sel:[0,1]
	v_pk_fma_f32 v[186:187], v[132:133], v[186:187], v[238:239]
	v_pk_fma_f32 v[66:67], v[186:187], s[42:43], v[154:155] op_sel_hi:[1,0,1]
	v_pk_add_f32 v[188:189], v[188:189], v[246:247] op_sel_hi:[1,0] neg_lo:[0,1] neg_hi:[0,1]
	v_pk_mul_f32 v[188:189], v[188:189], v[246:247] op_sel:[0,1]
	v_pk_fma_f32 v[188:189], v[134:135], v[188:189], v[240:241]
	v_pk_fma_f32 v[68:69], v[188:189], s[42:43], v[156:157] op_sel_hi:[1,0,1]
	v_pk_add_f32 v[190:191], v[190:191], v[246:247] op_sel_hi:[1,0] neg_lo:[0,1] neg_hi:[0,1]
	v_pk_mul_f32 v[190:191], v[190:191], v[246:247] op_sel:[0,1]
	v_pk_fma_f32 v[190:191], v[136:137], v[190:191], v[242:243]
	v_pk_fma_f32 v[70:71], v[190:191], s[42:43], v[158:159] op_sel_hi:[1,0,1]
	v_pk_add_f32 v[192:193], v[192:193], v[246:247] op_sel_hi:[1,0] neg_lo:[0,1] neg_hi:[0,1]
	v_pk_mul_f32 v[192:193], v[192:193], v[246:247] op_sel:[0,1]
	v_pk_fma_f32 v[192:193], v[138:139], v[192:193], v[244:245]
	v_pk_fma_f32 v[72:73], v[192:193], s[42:43], v[160:161] op_sel_hi:[1,0,1]
	global_store_dwordx4 v[150:151], v[66:69], off
	global_store_dwordx4 v[150:151], v[70:73], off offset:16
	v_pk_add_f32 v[194:195], v[194:195], v[248:249] op_sel_hi:[1,0] neg_lo:[0,1] neg_hi:[0,1]
	v_pk_mul_f32 v[194:195], v[194:195], v[248:249] op_sel:[0,1]
	v_pk_fma_f32 v[194:195], v[132:133], v[194:195], v[238:239]
	v_pk_fma_f32 v[74:75], v[194:195], s[42:43], v[162:163] op_sel_hi:[1,0,1]
	v_pk_add_f32 v[196:197], v[196:197], v[248:249] op_sel_hi:[1,0] neg_lo:[0,1] neg_hi:[0,1]
	v_pk_mul_f32 v[196:197], v[196:197], v[248:249] op_sel:[0,1]
	v_pk_fma_f32 v[196:197], v[134:135], v[196:197], v[240:241]
	v_pk_fma_f32 v[76:77], v[196:197], s[42:43], v[164:165] op_sel_hi:[1,0,1]
	v_pk_add_f32 v[198:199], v[198:199], v[248:249] op_sel_hi:[1,0] neg_lo:[0,1] neg_hi:[0,1]
	v_pk_mul_f32 v[198:199], v[198:199], v[248:249] op_sel:[0,1]
	v_pk_fma_f32 v[198:199], v[136:137], v[198:199], v[242:243]
	v_pk_fma_f32 v[78:79], v[198:199], s[42:43], v[166:167] op_sel_hi:[1,0,1]
	v_pk_add_f32 v[200:201], v[200:201], v[248:249] op_sel_hi:[1,0] neg_lo:[0,1] neg_hi:[0,1]
	v_pk_mul_f32 v[200:201], v[200:201], v[248:249] op_sel:[0,1]
	v_pk_fma_f32 v[200:201], v[138:139], v[200:201], v[244:245]
	v_pk_fma_f32 v[80:81], v[200:201], s[42:43], v[168:169] op_sel_hi:[1,0,1]
	global_store_dwordx4 v[220:221], v[74:77], off
	global_store_dwordx4 v[220:221], v[78:81], off offset:16
	v_pk_add_f32 v[202:203], v[202:203], v[250:251] op_sel_hi:[1,0] neg_lo:[0,1] neg_hi:[0,1]
	v_pk_mul_f32 v[202:203], v[202:203], v[250:251] op_sel:[0,1]
	v_pk_fma_f32 v[202:203], v[132:133], v[202:203], v[238:239]
	v_pk_fma_f32 v[82:83], v[202:203], s[42:43], v[170:171] op_sel_hi:[1,0,1]
	v_pk_add_f32 v[204:205], v[204:205], v[250:251] op_sel_hi:[1,0] neg_lo:[0,1] neg_hi:[0,1]
	v_pk_mul_f32 v[204:205], v[204:205], v[250:251] op_sel:[0,1]
	v_pk_fma_f32 v[204:205], v[134:135], v[204:205], v[240:241]
	v_pk_fma_f32 v[84:85], v[204:205], s[42:43], v[172:173] op_sel_hi:[1,0,1]
	v_pk_add_f32 v[206:207], v[206:207], v[250:251] op_sel_hi:[1,0] neg_lo:[0,1] neg_hi:[0,1]
	v_pk_mul_f32 v[206:207], v[206:207], v[250:251] op_sel:[0,1]
	v_pk_fma_f32 v[206:207], v[136:137], v[206:207], v[242:243]
	v_pk_fma_f32 v[86:87], v[206:207], s[42:43], v[174:175] op_sel_hi:[1,0,1]
	v_pk_add_f32 v[208:209], v[208:209], v[250:251] op_sel_hi:[1,0] neg_lo:[0,1] neg_hi:[0,1]
	v_pk_mul_f32 v[208:209], v[208:209], v[250:251] op_sel:[0,1]
	v_pk_fma_f32 v[208:209], v[138:139], v[208:209], v[244:245]
	v_pk_fma_f32 v[88:89], v[208:209], s[42:43], v[176:177] op_sel_hi:[1,0,1]
	global_store_dwordx4 v[222:223], v[82:85], off
	global_store_dwordx4 v[222:223], v[86:89], off offset:16
	v_pk_add_f32 v[210:211], v[210:211], v[218:219] op_sel_hi:[1,0] neg_lo:[0,1] neg_hi:[0,1]
	v_pk_mul_f32 v[210:211], v[210:211], v[218:219] op_sel:[0,1]
	v_pk_fma_f32 v[210:211], v[132:133], v[210:211], v[238:239]
	v_pk_fma_f32 v[90:91], v[210:211], s[42:43], v[178:179] op_sel_hi:[1,0,1]
	v_pk_add_f32 v[212:213], v[212:213], v[218:219] op_sel_hi:[1,0] neg_lo:[0,1] neg_hi:[0,1]
	v_pk_mul_f32 v[212:213], v[212:213], v[218:219] op_sel:[0,1]
	v_pk_fma_f32 v[212:213], v[134:135], v[212:213], v[240:241]
	v_pk_fma_f32 v[92:93], v[212:213], s[42:43], v[180:181] op_sel_hi:[1,0,1]
	v_pk_add_f32 v[214:215], v[214:215], v[218:219] op_sel_hi:[1,0] neg_lo:[0,1] neg_hi:[0,1]
	v_pk_mul_f32 v[214:215], v[214:215], v[218:219] op_sel:[0,1]
	v_pk_fma_f32 v[214:215], v[136:137], v[214:215], v[242:243]
	v_pk_fma_f32 v[94:95], v[214:215], s[42:43], v[182:183] op_sel_hi:[1,0,1]
	v_pk_add_f32 v[216:217], v[216:217], v[218:219] op_sel_hi:[1,0] neg_lo:[0,1] neg_hi:[0,1]
	v_pk_mul_f32 v[216:217], v[216:217], v[218:219] op_sel:[0,1]
	v_pk_fma_f32 v[216:217], v[138:139], v[216:217], v[244:245]
	v_pk_fma_f32 v[96:97], v[216:217], s[42:43], v[184:185] op_sel_hi:[1,0,1]
	global_store_dwordx4 v[224:225], v[90:93], off
	global_store_dwordx4 v[224:225], v[94:97], off offset:16
	s_mov_b32 s38, 0x80000
	v_lshl_add_u64 v[150:151], v[230:231], 0, s[38:39]
	v_lshl_add_u64 v[220:221], v[150:151], 0, s[36:37]
	v_lshl_add_u64 v[222:223], v[220:221], 0, s[36:37]
	v_lshl_add_u64 v[224:225], v[222:223], 0, s[36:37]
	global_load_dwordx2 v[246:247], v227, s[52:53] offset:1024
	global_load_dwordx2 v[248:249], v227, s[52:53] offset:1280
	global_load_dwordx2 v[250:251], v227, s[52:53] offset:1536
	global_load_dwordx2 v[218:219], v227, s[52:53] offset:1792
	global_load_dwordx4 v[132:135], v226, s[70:71] offset:0
	global_load_dwordx4 v[136:139], v226, s[70:71] offset:16
	global_load_dwordx4 v[238:241], v226, s[74:75] offset:0
	global_load_dwordx4 v[242:245], v226, s[74:75] offset:16
	global_load_dwordx4 v[186:189], v[150:151], off
	global_load_dwordx4 v[190:193], v[150:151], off offset:16
	global_load_dwordx4 v[194:197], v[220:221], off
	global_load_dwordx4 v[198:201], v[220:221], off offset:16
	global_load_dwordx4 v[202:205], v[222:223], off
	global_load_dwordx4 v[206:209], v[222:223], off offset:16
	global_load_dwordx4 v[210:213], v[224:225], off
	global_load_dwordx4 v[214:217], v[224:225], off offset:16
	ds_write2st64_b32 v153, v34, v35 offset1:2
	ds_write2st64_b32 v153, v36, v37 offset0:4 offset1:6
	ds_write2st64_b32 v149, v38, v39 offset1:2
	ds_write2st64_b32 v149, v40, v41 offset0:4 offset1:6
	ds_write2st64_b32 v153, v42, v43 offset0:32 offset1:34
	ds_write2st64_b32 v153, v44, v45 offset0:36 offset1:38
	ds_write2st64_b32 v149, v46, v47 offset0:32 offset1:34
	ds_write2st64_b32 v149, v48, v49 offset0:36 offset1:38
	ds_write2st64_b32 v153, v50, v51 offset0:64 offset1:66
	ds_write2st64_b32 v153, v52, v53 offset0:68 offset1:70
	ds_write2st64_b32 v149, v54, v55 offset0:64 offset1:66
	ds_write2st64_b32 v149, v56, v57 offset0:68 offset1:70
	ds_write2st64_b32 v153, v58, v59 offset0:96 offset1:98
	ds_write2st64_b32 v153, v60, v61 offset0:100 offset1:102
	ds_write2st64_b32 v149, v62, v63 offset0:96 offset1:98
	ds_write2st64_b32 v149, v64, v65 offset0:100 offset1:102
	s_waitcnt lgkmcnt(0)
	s_barrier
	ds_read_b128 v[154:157], v147
	ds_read_b128 v[158:161], v148
	ds_read_b128 v[162:165], v146
	ds_read_b128 v[166:169], v145
	ds_read_b128 v[170:173], v144
	ds_read_b128 v[174:177], v143
	ds_read_b128 v[178:181], v141
	ds_read_b128 v[182:185], v140
	s_waitcnt vmcnt(0) lgkmcnt(0)
	s_barrier
	v_pk_add_f32 v[186:187], v[186:187], v[246:247] op_sel_hi:[1,0] neg_lo:[0,1] neg_hi:[0,1]
	v_pk_mul_f32 v[186:187], v[186:187], v[246:247] op_sel:[0,1]
	v_pk_fma_f32 v[186:187], v[132:133], v[186:187], v[238:239]
	v_pk_fma_f32 v[34:35], v[186:187], s[42:43], v[154:155] op_sel_hi:[1,0,1]
	v_pk_add_f32 v[188:189], v[188:189], v[246:247] op_sel_hi:[1,0] neg_lo:[0,1] neg_hi:[0,1]
	v_pk_mul_f32 v[188:189], v[188:189], v[246:247] op_sel:[0,1]
	v_pk_fma_f32 v[188:189], v[134:135], v[188:189], v[240:241]
	v_pk_fma_f32 v[36:37], v[188:189], s[42:43], v[156:157] op_sel_hi:[1,0,1]
	v_pk_add_f32 v[190:191], v[190:191], v[246:247] op_sel_hi:[1,0] neg_lo:[0,1] neg_hi:[0,1]
	v_pk_mul_f32 v[190:191], v[190:191], v[246:247] op_sel:[0,1]
	v_pk_fma_f32 v[190:191], v[136:137], v[190:191], v[242:243]
	v_pk_fma_f32 v[38:39], v[190:191], s[42:43], v[158:159] op_sel_hi:[1,0,1]
	v_pk_add_f32 v[192:193], v[192:193], v[246:247] op_sel_hi:[1,0] neg_lo:[0,1] neg_hi:[0,1]
	v_pk_mul_f32 v[192:193], v[192:193], v[246:247] op_sel:[0,1]
	v_pk_fma_f32 v[192:193], v[138:139], v[192:193], v[244:245]
	v_pk_fma_f32 v[40:41], v[192:193], s[42:43], v[160:161] op_sel_hi:[1,0,1]
	global_store_dwordx4 v[150:151], v[34:37], off
	global_store_dwordx4 v[150:151], v[38:41], off offset:16
	v_pk_add_f32 v[194:195], v[194:195], v[248:249] op_sel_hi:[1,0] neg_lo:[0,1] neg_hi:[0,1]
	v_pk_mul_f32 v[194:195], v[194:195], v[248:249] op_sel:[0,1]
	v_pk_fma_f32 v[194:195], v[132:133], v[194:195], v[238:239]
	v_pk_fma_f32 v[42:43], v[194:195], s[42:43], v[162:163] op_sel_hi:[1,0,1]
	v_pk_add_f32 v[196:197], v[196:197], v[248:249] op_sel_hi:[1,0] neg_lo:[0,1] neg_hi:[0,1]
	v_pk_mul_f32 v[196:197], v[196:197], v[248:249] op_sel:[0,1]
	v_pk_fma_f32 v[196:197], v[134:135], v[196:197], v[240:241]
	v_pk_fma_f32 v[44:45], v[196:197], s[42:43], v[164:165] op_sel_hi:[1,0,1]
	v_pk_add_f32 v[198:199], v[198:199], v[248:249] op_sel_hi:[1,0] neg_lo:[0,1] neg_hi:[0,1]
	v_pk_mul_f32 v[198:199], v[198:199], v[248:249] op_sel:[0,1]
	v_pk_fma_f32 v[198:199], v[136:137], v[198:199], v[242:243]
	v_pk_fma_f32 v[46:47], v[198:199], s[42:43], v[166:167] op_sel_hi:[1,0,1]
	v_pk_add_f32 v[200:201], v[200:201], v[248:249] op_sel_hi:[1,0] neg_lo:[0,1] neg_hi:[0,1]
	v_pk_mul_f32 v[200:201], v[200:201], v[248:249] op_sel:[0,1]
	v_pk_fma_f32 v[200:201], v[138:139], v[200:201], v[244:245]
	v_pk_fma_f32 v[48:49], v[200:201], s[42:43], v[168:169] op_sel_hi:[1,0,1]
	global_store_dwordx4 v[220:221], v[42:45], off
	global_store_dwordx4 v[220:221], v[46:49], off offset:16
	v_pk_add_f32 v[202:203], v[202:203], v[250:251] op_sel_hi:[1,0] neg_lo:[0,1] neg_hi:[0,1]
	v_pk_mul_f32 v[202:203], v[202:203], v[250:251] op_sel:[0,1]
	v_pk_fma_f32 v[202:203], v[132:133], v[202:203], v[238:239]
	v_pk_fma_f32 v[50:51], v[202:203], s[42:43], v[170:171] op_sel_hi:[1,0,1]
	v_pk_add_f32 v[204:205], v[204:205], v[250:251] op_sel_hi:[1,0] neg_lo:[0,1] neg_hi:[0,1]
	v_pk_mul_f32 v[204:205], v[204:205], v[250:251] op_sel:[0,1]
	v_pk_fma_f32 v[204:205], v[134:135], v[204:205], v[240:241]
	v_pk_fma_f32 v[52:53], v[204:205], s[42:43], v[172:173] op_sel_hi:[1,0,1]
	v_pk_add_f32 v[206:207], v[206:207], v[250:251] op_sel_hi:[1,0] neg_lo:[0,1] neg_hi:[0,1]
	v_pk_mul_f32 v[206:207], v[206:207], v[250:251] op_sel:[0,1]
	v_pk_fma_f32 v[206:207], v[136:137], v[206:207], v[242:243]
	v_pk_fma_f32 v[54:55], v[206:207], s[42:43], v[174:175] op_sel_hi:[1,0,1]
	v_pk_add_f32 v[208:209], v[208:209], v[250:251] op_sel_hi:[1,0] neg_lo:[0,1] neg_hi:[0,1]
	v_pk_mul_f32 v[208:209], v[208:209], v[250:251] op_sel:[0,1]
	v_pk_fma_f32 v[208:209], v[138:139], v[208:209], v[244:245]
	v_pk_fma_f32 v[56:57], v[208:209], s[42:43], v[176:177] op_sel_hi:[1,0,1]
	global_store_dwordx4 v[222:223], v[50:53], off
	global_store_dwordx4 v[222:223], v[54:57], off offset:16
	v_pk_add_f32 v[210:211], v[210:211], v[218:219] op_sel_hi:[1,0] neg_lo:[0,1] neg_hi:[0,1]
	v_pk_mul_f32 v[210:211], v[210:211], v[218:219] op_sel:[0,1]
	v_pk_fma_f32 v[210:211], v[132:133], v[210:211], v[238:239]
	v_pk_fma_f32 v[58:59], v[210:211], s[42:43], v[178:179] op_sel_hi:[1,0,1]
	v_pk_add_f32 v[212:213], v[212:213], v[218:219] op_sel_hi:[1,0] neg_lo:[0,1] neg_hi:[0,1]
	v_pk_mul_f32 v[212:213], v[212:213], v[218:219] op_sel:[0,1]
	v_pk_fma_f32 v[212:213], v[134:135], v[212:213], v[240:241]
	v_pk_fma_f32 v[60:61], v[212:213], s[42:43], v[180:181] op_sel_hi:[1,0,1]
	v_pk_add_f32 v[214:215], v[214:215], v[218:219] op_sel_hi:[1,0] neg_lo:[0,1] neg_hi:[0,1]
	v_pk_mul_f32 v[214:215], v[214:215], v[218:219] op_sel:[0,1]
	v_pk_fma_f32 v[214:215], v[136:137], v[214:215], v[242:243]
	v_pk_fma_f32 v[62:63], v[214:215], s[42:43], v[182:183] op_sel_hi:[1,0,1]
	v_pk_add_f32 v[216:217], v[216:217], v[218:219] op_sel_hi:[1,0] neg_lo:[0,1] neg_hi:[0,1]
	v_pk_mul_f32 v[216:217], v[216:217], v[218:219] op_sel:[0,1]
	v_pk_fma_f32 v[216:217], v[138:139], v[216:217], v[244:245]
	v_pk_fma_f32 v[64:65], v[216:217], s[42:43], v[184:185] op_sel_hi:[1,0,1]
	global_store_dwordx4 v[224:225], v[58:61], off
	global_store_dwordx4 v[224:225], v[62:65], off offset:16
	s_mov_b32 s38, 0x80200
	v_lshl_add_u64 v[150:151], v[230:231], 0, s[38:39]
	v_lshl_add_u64 v[220:221], v[150:151], 0, s[36:37]
	v_lshl_add_u64 v[222:223], v[220:221], 0, s[36:37]
	v_lshl_add_u64 v[224:225], v[222:223], 0, s[36:37]
	global_load_dwordx2 v[246:247], v227, s[52:53] offset:1024
	global_load_dwordx2 v[248:249], v227, s[52:53] offset:1280
	global_load_dwordx2 v[250:251], v227, s[52:53] offset:1536
	global_load_dwordx2 v[218:219], v227, s[52:53] offset:1792
	global_load_dwordx4 v[132:135], v226, s[70:71] offset:512
	global_load_dwordx4 v[136:139], v226, s[70:71] offset:528
	global_load_dwordx4 v[238:241], v226, s[74:75] offset:512
	global_load_dwordx4 v[242:245], v226, s[74:75] offset:528
	global_load_dwordx4 v[186:189], v[150:151], off
	global_load_dwordx4 v[190:193], v[150:151], off offset:16
	global_load_dwordx4 v[194:197], v[220:221], off
	global_load_dwordx4 v[198:201], v[220:221], off offset:16
	global_load_dwordx4 v[202:205], v[222:223], off
	global_load_dwordx4 v[206:209], v[222:223], off offset:16
	global_load_dwordx4 v[210:213], v[224:225], off
	global_load_dwordx4 v[214:217], v[224:225], off offset:16
	ds_write2st64_b32 v153, v2, v3 offset1:2
	ds_write2st64_b32 v153, v4, v5 offset0:4 offset1:6
	ds_write2st64_b32 v149, v6, v7 offset1:2
	ds_write2st64_b32 v149, v8, v9 offset0:4 offset1:6
	ds_write2st64_b32 v153, v10, v11 offset0:32 offset1:34
	ds_write2st64_b32 v153, v12, v13 offset0:36 offset1:38
	ds_write2st64_b32 v149, v14, v15 offset0:32 offset1:34
	ds_write2st64_b32 v149, v16, v17 offset0:36 offset1:38
	ds_write2st64_b32 v153, v18, v19 offset0:64 offset1:66
	ds_write2st64_b32 v153, v20, v21 offset0:68 offset1:70
	ds_write2st64_b32 v149, v22, v23 offset0:64 offset1:66
	ds_write2st64_b32 v149, v24, v25 offset0:68 offset1:70
	ds_write2st64_b32 v153, v26, v27 offset0:96 offset1:98
	ds_write2st64_b32 v153, v28, v29 offset0:100 offset1:102
	ds_write2st64_b32 v149, v30, v31 offset0:96 offset1:98
	ds_write2st64_b32 v149, v32, v33 offset0:100 offset1:102
	s_waitcnt lgkmcnt(0)
	s_barrier
	ds_read_b128 v[154:157], v147
	ds_read_b128 v[158:161], v148
	ds_read_b128 v[162:165], v146
	ds_read_b128 v[166:169], v145
	ds_read_b128 v[170:173], v144
	ds_read_b128 v[174:177], v143
	ds_read_b128 v[178:181], v141
	ds_read_b128 v[182:185], v140
	s_waitcnt vmcnt(0) lgkmcnt(0)
	v_pk_add_f32 v[186:187], v[186:187], v[246:247] op_sel_hi:[1,0] neg_lo:[0,1] neg_hi:[0,1]
	v_pk_mul_f32 v[186:187], v[186:187], v[246:247] op_sel:[0,1]
	v_pk_fma_f32 v[186:187], v[132:133], v[186:187], v[238:239]
	v_pk_fma_f32 v[2:3], v[186:187], s[42:43], v[154:155] op_sel_hi:[1,0,1]
	v_pk_add_f32 v[188:189], v[188:189], v[246:247] op_sel_hi:[1,0] neg_lo:[0,1] neg_hi:[0,1]
	v_pk_mul_f32 v[188:189], v[188:189], v[246:247] op_sel:[0,1]
	v_pk_fma_f32 v[188:189], v[134:135], v[188:189], v[240:241]
	v_pk_fma_f32 v[4:5], v[188:189], s[42:43], v[156:157] op_sel_hi:[1,0,1]
	v_pk_add_f32 v[190:191], v[190:191], v[246:247] op_sel_hi:[1,0] neg_lo:[0,1] neg_hi:[0,1]
	v_pk_mul_f32 v[190:191], v[190:191], v[246:247] op_sel:[0,1]
	v_pk_fma_f32 v[190:191], v[136:137], v[190:191], v[242:243]
	v_pk_fma_f32 v[6:7], v[190:191], s[42:43], v[158:159] op_sel_hi:[1,0,1]
	v_pk_add_f32 v[192:193], v[192:193], v[246:247] op_sel_hi:[1,0] neg_lo:[0,1] neg_hi:[0,1]
	v_pk_mul_f32 v[192:193], v[192:193], v[246:247] op_sel:[0,1]
	v_pk_fma_f32 v[192:193], v[138:139], v[192:193], v[244:245]
	v_pk_fma_f32 v[8:9], v[192:193], s[42:43], v[160:161] op_sel_hi:[1,0,1]
	global_store_dwordx4 v[150:151], v[2:5], off
	global_store_dwordx4 v[150:151], v[6:9], off offset:16
	v_pk_add_f32 v[194:195], v[194:195], v[248:249] op_sel_hi:[1,0] neg_lo:[0,1] neg_hi:[0,1]
	v_pk_mul_f32 v[194:195], v[194:195], v[248:249] op_sel:[0,1]
	v_pk_fma_f32 v[194:195], v[132:133], v[194:195], v[238:239]
	v_pk_fma_f32 v[10:11], v[194:195], s[42:43], v[162:163] op_sel_hi:[1,0,1]
	v_pk_add_f32 v[196:197], v[196:197], v[248:249] op_sel_hi:[1,0] neg_lo:[0,1] neg_hi:[0,1]
	v_pk_mul_f32 v[196:197], v[196:197], v[248:249] op_sel:[0,1]
	v_pk_fma_f32 v[196:197], v[134:135], v[196:197], v[240:241]
	v_pk_fma_f32 v[12:13], v[196:197], s[42:43], v[164:165] op_sel_hi:[1,0,1]
	v_pk_add_f32 v[198:199], v[198:199], v[248:249] op_sel_hi:[1,0] neg_lo:[0,1] neg_hi:[0,1]
	v_pk_mul_f32 v[198:199], v[198:199], v[248:249] op_sel:[0,1]
	v_pk_fma_f32 v[198:199], v[136:137], v[198:199], v[242:243]
	v_pk_fma_f32 v[14:15], v[198:199], s[42:43], v[166:167] op_sel_hi:[1,0,1]
	v_pk_add_f32 v[200:201], v[200:201], v[248:249] op_sel_hi:[1,0] neg_lo:[0,1] neg_hi:[0,1]
	v_pk_mul_f32 v[200:201], v[200:201], v[248:249] op_sel:[0,1]
	v_pk_fma_f32 v[200:201], v[138:139], v[200:201], v[244:245]
	v_pk_fma_f32 v[16:17], v[200:201], s[42:43], v[168:169] op_sel_hi:[1,0,1]
	global_store_dwordx4 v[220:221], v[10:13], off
	global_store_dwordx4 v[220:221], v[14:17], off offset:16
	v_pk_add_f32 v[202:203], v[202:203], v[250:251] op_sel_hi:[1,0] neg_lo:[0,1] neg_hi:[0,1]
	v_pk_mul_f32 v[202:203], v[202:203], v[250:251] op_sel:[0,1]
	v_pk_fma_f32 v[202:203], v[132:133], v[202:203], v[238:239]
	v_pk_fma_f32 v[18:19], v[202:203], s[42:43], v[170:171] op_sel_hi:[1,0,1]
	v_pk_add_f32 v[204:205], v[204:205], v[250:251] op_sel_hi:[1,0] neg_lo:[0,1] neg_hi:[0,1]
	v_pk_mul_f32 v[204:205], v[204:205], v[250:251] op_sel:[0,1]
	v_pk_fma_f32 v[204:205], v[134:135], v[204:205], v[240:241]
	v_pk_fma_f32 v[20:21], v[204:205], s[42:43], v[172:173] op_sel_hi:[1,0,1]
	v_pk_add_f32 v[206:207], v[206:207], v[250:251] op_sel_hi:[1,0] neg_lo:[0,1] neg_hi:[0,1]
	v_pk_mul_f32 v[206:207], v[206:207], v[250:251] op_sel:[0,1]
	v_pk_fma_f32 v[206:207], v[136:137], v[206:207], v[242:243]
	v_pk_fma_f32 v[22:23], v[206:207], s[42:43], v[174:175] op_sel_hi:[1,0,1]
	v_pk_add_f32 v[208:209], v[208:209], v[250:251] op_sel_hi:[1,0] neg_lo:[0,1] neg_hi:[0,1]
	v_pk_mul_f32 v[208:209], v[208:209], v[250:251] op_sel:[0,1]
	v_pk_fma_f32 v[208:209], v[138:139], v[208:209], v[244:245]
	v_pk_fma_f32 v[24:25], v[208:209], s[42:43], v[176:177] op_sel_hi:[1,0,1]
	global_store_dwordx4 v[222:223], v[18:21], off
	global_store_dwordx4 v[222:223], v[22:25], off offset:16
	v_pk_add_f32 v[210:211], v[210:211], v[218:219] op_sel_hi:[1,0] neg_lo:[0,1] neg_hi:[0,1]
	v_pk_mul_f32 v[210:211], v[210:211], v[218:219] op_sel:[0,1]
	v_pk_fma_f32 v[210:211], v[132:133], v[210:211], v[238:239]
	v_pk_fma_f32 v[26:27], v[210:211], s[42:43], v[178:179] op_sel_hi:[1,0,1]
	v_pk_add_f32 v[212:213], v[212:213], v[218:219] op_sel_hi:[1,0] neg_lo:[0,1] neg_hi:[0,1]
	v_pk_mul_f32 v[212:213], v[212:213], v[218:219] op_sel:[0,1]
	v_pk_fma_f32 v[212:213], v[134:135], v[212:213], v[240:241]
	v_pk_fma_f32 v[28:29], v[212:213], s[42:43], v[180:181] op_sel_hi:[1,0,1]
	v_pk_add_f32 v[214:215], v[214:215], v[218:219] op_sel_hi:[1,0] neg_lo:[0,1] neg_hi:[0,1]
	v_pk_mul_f32 v[214:215], v[214:215], v[218:219] op_sel:[0,1]
	v_pk_fma_f32 v[214:215], v[136:137], v[214:215], v[242:243]
	v_pk_fma_f32 v[30:31], v[214:215], s[42:43], v[182:183] op_sel_hi:[1,0,1]
	v_pk_add_f32 v[216:217], v[216:217], v[218:219] op_sel_hi:[1,0] neg_lo:[0,1] neg_hi:[0,1]
	v_pk_mul_f32 v[216:217], v[216:217], v[218:219] op_sel:[0,1]
	v_pk_fma_f32 v[216:217], v[138:139], v[216:217], v[244:245]
	v_pk_fma_f32 v[32:33], v[216:217], s[42:43], v[184:185] op_sel_hi:[1,0,1]
	global_store_dwordx4 v[224:225], v[26:29], off
	global_store_dwordx4 v[224:225], v[30:33], off offset:16
	v_readlane_b32 s70, v253, 18
	v_readlane_b32 s71, v253, 19
	v_readlane_b32 s74, v253, 20
	v_readlane_b32 s75, v253, 21
	v_lshrrev_b64 v[222:223], 1, v[228:229]
	v_lshl_add_u64 v[222:223], s[60:61], 0, v[222:223]
	s_nop 2
	global_load_dwordx4 v[186:189], v226, s[70:71] offset:0
	global_load_dwordx4 v[190:193], v226, s[70:71] offset:16
	global_load_dwordx4 v[194:197], v226, s[70:71] offset:512
	global_load_dwordx4 v[198:201], v226, s[70:71] offset:528
	global_load_dwordx4 v[202:205], v226, s[74:75] offset:0
	global_load_dwordx4 v[206:209], v226, s[74:75] offset:16
	global_load_dwordx4 v[210:213], v226, s[74:75] offset:512
	global_load_dwordx4 v[214:217], v226, s[74:75] offset:528
	v_pk_add_f32 v[154:155], v[98:99], v[100:101]
	v_pk_add_f32 v[156:157], v[106:107], v[108:109]
	v_pk_add_f32 v[158:159], v[114:115], v[116:117]
	v_pk_add_f32 v[160:161], v[122:123], v[124:125]
	v_pk_add_f32 v[162:163], v[34:35], v[36:37]
	v_pk_add_f32 v[164:165], v[42:43], v[44:45]
	v_pk_add_f32 v[166:167], v[50:51], v[52:53]
	v_pk_add_f32 v[168:169], v[58:59], v[60:61]
	v_pk_add_f32 v[154:155], v[154:155], v[102:103]
	v_pk_add_f32 v[156:157], v[156:157], v[110:111]
	v_pk_add_f32 v[158:159], v[158:159], v[118:119]
	v_pk_add_f32 v[160:161], v[160:161], v[126:127]
	v_pk_add_f32 v[162:163], v[162:163], v[38:39]
	v_pk_add_f32 v[164:165], v[164:165], v[46:47]
	v_pk_add_f32 v[166:167], v[166:167], v[54:55]
	v_pk_add_f32 v[168:169], v[168:169], v[62:63]
	v_pk_add_f32 v[154:155], v[154:155], v[104:105]
	v_pk_add_f32 v[156:157], v[156:157], v[112:113]
	v_pk_add_f32 v[158:159], v[158:159], v[120:121]
	v_pk_add_f32 v[160:161], v[160:161], v[128:129]
	v_pk_add_f32 v[162:163], v[162:163], v[40:41]
	v_pk_add_f32 v[164:165], v[164:165], v[48:49]
	v_pk_add_f32 v[166:167], v[166:167], v[56:57]
	v_pk_add_f32 v[168:169], v[168:169], v[64:65]
	v_pk_add_f32 v[154:155], v[154:155], v[66:67]
	v_pk_add_f32 v[156:157], v[156:157], v[74:75]
	v_pk_add_f32 v[158:159], v[158:159], v[82:83]
	v_pk_add_f32 v[160:161], v[160:161], v[90:91]
	v_pk_add_f32 v[162:163], v[162:163], v[2:3]
	v_pk_add_f32 v[164:165], v[164:165], v[10:11]
	v_pk_add_f32 v[166:167], v[166:167], v[18:19]
	v_pk_add_f32 v[168:169], v[168:169], v[26:27]
	v_pk_add_f32 v[154:155], v[154:155], v[68:69]
	v_pk_add_f32 v[156:157], v[156:157], v[76:77]
	v_pk_add_f32 v[158:159], v[158:159], v[84:85]
	v_pk_add_f32 v[160:161], v[160:161], v[92:93]
	v_pk_add_f32 v[162:163], v[162:163], v[4:5]
	v_pk_add_f32 v[164:165], v[164:165], v[12:13]
	v_pk_add_f32 v[166:167], v[166:167], v[20:21]
	v_pk_add_f32 v[168:169], v[168:169], v[28:29]
	v_pk_add_f32 v[154:155], v[154:155], v[70:71]
	v_pk_add_f32 v[156:157], v[156:157], v[78:79]
	v_pk_add_f32 v[158:159], v[158:159], v[86:87]
	v_pk_add_f32 v[160:161], v[160:161], v[94:95]
	v_pk_add_f32 v[162:163], v[162:163], v[6:7]
	v_pk_add_f32 v[164:165], v[164:165], v[14:15]
	v_pk_add_f32 v[166:167], v[166:167], v[22:23]
	v_pk_add_f32 v[168:169], v[168:169], v[30:31]
	v_pk_add_f32 v[154:155], v[154:155], v[72:73]
	v_pk_add_f32 v[156:157], v[156:157], v[80:81]
	v_pk_add_f32 v[158:159], v[158:159], v[88:89]
	v_pk_add_f32 v[160:161], v[160:161], v[96:97]
	v_pk_add_f32 v[162:163], v[162:163], v[8:9]
	v_pk_add_f32 v[164:165], v[164:165], v[16:17]
	v_pk_add_f32 v[166:167], v[166:167], v[24:25]
	v_pk_add_f32 v[168:169], v[168:169], v[32:33]
	v_add_f32_e32 v132, v154, v155
	v_add_f32_e32 v134, v156, v157
	v_add_f32_e32 v136, v158, v159
	v_add_f32_e32 v138, v160, v161
	v_add_f32_e32 v232, v162, v163
	v_add_f32_e32 v234, v164, v165
	v_add_f32_e32 v236, v166, v167
	v_add_f32_e32 v150, v168, v169
	v_add_f32_dpp v132, v132, v132 quad_perm:[1,0,3,2] row_mask:0xf bank_mask:0xf
	v_add_f32_dpp v134, v134, v134 quad_perm:[1,0,3,2] row_mask:0xf bank_mask:0xf
	v_add_f32_dpp v136, v136, v136 quad_perm:[1,0,3,2] row_mask:0xf bank_mask:0xf
	v_add_f32_dpp v138, v138, v138 quad_perm:[1,0,3,2] row_mask:0xf bank_mask:0xf
	v_add_f32_dpp v232, v232, v232 quad_perm:[1,0,3,2] row_mask:0xf bank_mask:0xf
	v_add_f32_dpp v234, v234, v234 quad_perm:[1,0,3,2] row_mask:0xf bank_mask:0xf
	v_add_f32_dpp v236, v236, v236 quad_perm:[1,0,3,2] row_mask:0xf bank_mask:0xf
	v_add_f32_dpp v150, v150, v150 quad_perm:[1,0,3,2] row_mask:0xf bank_mask:0xf
	v_add_f32_dpp v132, v132, v132 quad_perm:[2,3,0,1] row_mask:0xf bank_mask:0xf
	v_add_f32_dpp v134, v134, v134 quad_perm:[2,3,0,1] row_mask:0xf bank_mask:0xf
	v_add_f32_dpp v136, v136, v136 quad_perm:[2,3,0,1] row_mask:0xf bank_mask:0xf
	v_add_f32_dpp v138, v138, v138 quad_perm:[2,3,0,1] row_mask:0xf bank_mask:0xf
	v_add_f32_dpp v232, v232, v232 quad_perm:[2,3,0,1] row_mask:0xf bank_mask:0xf
	v_add_f32_dpp v234, v234, v234 quad_perm:[2,3,0,1] row_mask:0xf bank_mask:0xf
	v_add_f32_dpp v236, v236, v236 quad_perm:[2,3,0,1] row_mask:0xf bank_mask:0xf
	v_add_f32_dpp v150, v150, v150 quad_perm:[2,3,0,1] row_mask:0xf bank_mask:0xf
	v_add_f32_dpp v132, v132, v132 row_half_mirror row_mask:0xf bank_mask:0xf
	v_add_f32_dpp v134, v134, v134 row_half_mirror row_mask:0xf bank_mask:0xf
	v_add_f32_dpp v136, v136, v136 row_half_mirror row_mask:0xf bank_mask:0xf
	v_add_f32_dpp v138, v138, v138 row_half_mirror row_mask:0xf bank_mask:0xf
	v_add_f32_dpp v232, v232, v232 row_half_mirror row_mask:0xf bank_mask:0xf
	v_add_f32_dpp v234, v234, v234 row_half_mirror row_mask:0xf bank_mask:0xf
	v_add_f32_dpp v236, v236, v236 row_half_mirror row_mask:0xf bank_mask:0xf
	v_add_f32_dpp v150, v150, v150 row_half_mirror row_mask:0xf bank_mask:0xf
	v_add_f32_dpp v132, v132, v132 row_mirror row_mask:0xf bank_mask:0xf
	v_add_f32_dpp v134, v134, v134 row_mirror row_mask:0xf bank_mask:0xf
	v_add_f32_dpp v136, v136, v136 row_mirror row_mask:0xf bank_mask:0xf
	v_add_f32_dpp v138, v138, v138 row_mirror row_mask:0xf bank_mask:0xf
	v_add_f32_dpp v232, v232, v232 row_mirror row_mask:0xf bank_mask:0xf
	v_add_f32_dpp v234, v234, v234 row_mirror row_mask:0xf bank_mask:0xf
	v_add_f32_dpp v236, v236, v236 row_mirror row_mask:0xf bank_mask:0xf
	v_add_f32_dpp v150, v150, v150 row_mirror row_mask:0xf bank_mask:0xf
	v_mul_f32_e32 v132, 0x3b800000, v132
	v_mul_f32_e32 v134, 0x3b800000, v134
	v_mul_f32_e32 v136, 0x3b800000, v136
	v_mul_f32_e32 v138, 0x3b800000, v138
	v_mul_f32_e32 v232, 0x3b800000, v232
	v_mul_f32_e32 v234, 0x3b800000, v234
	v_mul_f32_e32 v236, 0x3b800000, v236
	v_mul_f32_e32 v150, 0x3b800000, v150
	v_pk_add_f32 v[218:219], v[98:99], v[132:133] op_sel_hi:[1,0] neg_lo:[0,1] neg_hi:[0,1]
	v_pk_mul_f32 v[170:171], v[218:219], v[218:219]
	v_pk_add_f32 v[220:221], v[106:107], v[134:135] op_sel_hi:[1,0] neg_lo:[0,1] neg_hi:[0,1]
	v_pk_mul_f32 v[172:173], v[220:221], v[220:221]
	v_pk_add_f32 v[218:219], v[114:115], v[136:137] op_sel_hi:[1,0] neg_lo:[0,1] neg_hi:[0,1]
	v_pk_mul_f32 v[174:175], v[218:219], v[218:219]
	v_pk_add_f32 v[220:221], v[122:123], v[138:139] op_sel_hi:[1,0] neg_lo:[0,1] neg_hi:[0,1]
	v_pk_mul_f32 v[176:177], v[220:221], v[220:221]
	v_pk_add_f32 v[218:219], v[34:35], v[232:233] op_sel_hi:[1,0] neg_lo:[0,1] neg_hi:[0,1]
	v_pk_mul_f32 v[178:179], v[218:219], v[218:219]
	v_pk_add_f32 v[220:221], v[42:43], v[234:235] op_sel_hi:[1,0] neg_lo:[0,1] neg_hi:[0,1]
	v_pk_mul_f32 v[180:181], v[220:221], v[220:221]
	v_pk_add_f32 v[218:219], v[50:51], v[236:237] op_sel_hi:[1,0] neg_lo:[0,1] neg_hi:[0,1]
	v_pk_mul_f32 v[182:183], v[218:219], v[218:219]
	v_pk_add_f32 v[220:221], v[58:59], v[150:151] op_sel_hi:[1,0] neg_lo:[0,1] neg_hi:[0,1]
	v_pk_mul_f32 v[184:185], v[220:221], v[220:221]
	v_pk_add_f32 v[218:219], v[100:101], v[132:133] op_sel_hi:[1,0] neg_lo:[0,1] neg_hi:[0,1]
	v_pk_fma_f32 v[170:171], v[218:219], v[218:219], v[170:171]
	v_pk_add_f32 v[220:221], v[108:109], v[134:135] op_sel_hi:[1,0] neg_lo:[0,1] neg_hi:[0,1]
	v_pk_fma_f32 v[172:173], v[220:221], v[220:221], v[172:173]
	v_pk_add_f32 v[218:219], v[116:117], v[136:137] op_sel_hi:[1,0] neg_lo:[0,1] neg_hi:[0,1]
	v_pk_fma_f32 v[174:175], v[218:219], v[218:219], v[174:175]
	v_pk_add_f32 v[220:221], v[124:125], v[138:139] op_sel_hi:[1,0] neg_lo:[0,1] neg_hi:[0,1]
	v_pk_fma_f32 v[176:177], v[220:221], v[220:221], v[176:177]
	v_pk_add_f32 v[218:219], v[36:37], v[232:233] op_sel_hi:[1,0] neg_lo:[0,1] neg_hi:[0,1]
	v_pk_fma_f32 v[178:179], v[218:219], v[218:219], v[178:179]
	v_pk_add_f32 v[220:221], v[44:45], v[234:235] op_sel_hi:[1,0] neg_lo:[0,1] neg_hi:[0,1]
	v_pk_fma_f32 v[180:181], v[220:221], v[220:221], v[180:181]
	v_pk_add_f32 v[218:219], v[52:53], v[236:237] op_sel_hi:[1,0] neg_lo:[0,1] neg_hi:[0,1]
	v_pk_fma_f32 v[182:183], v[218:219], v[218:219], v[182:183]
	v_pk_add_f32 v[220:221], v[60:61], v[150:151] op_sel_hi:[1,0] neg_lo:[0,1] neg_hi:[0,1]
	v_pk_fma_f32 v[184:185], v[220:221], v[220:221], v[184:185]
	v_pk_add_f32 v[218:219], v[102:103], v[132:133] op_sel_hi:[1,0] neg_lo:[0,1] neg_hi:[0,1]
	v_pk_fma_f32 v[170:171], v[218:219], v[218:219], v[170:171]
	v_pk_add_f32 v[220:221], v[110:111], v[134:135] op_sel_hi:[1,0] neg_lo:[0,1] neg_hi:[0,1]
	v_pk_fma_f32 v[172:173], v[220:221], v[220:221], v[172:173]
	v_pk_add_f32 v[218:219], v[118:119], v[136:137] op_sel_hi:[1,0] neg_lo:[0,1] neg_hi:[0,1]
	v_pk_fma_f32 v[174:175], v[218:219], v[218:219], v[174:175]
	v_pk_add_f32 v[220:221], v[126:127], v[138:139] op_sel_hi:[1,0] neg_lo:[0,1] neg_hi:[0,1]
	v_pk_fma_f32 v[176:177], v[220:221], v[220:221], v[176:177]
	v_pk_add_f32 v[218:219], v[38:39], v[232:233] op_sel_hi:[1,0] neg_lo:[0,1] neg_hi:[0,1]
	v_pk_fma_f32 v[178:179], v[218:219], v[218:219], v[178:179]
	v_pk_add_f32 v[220:221], v[46:47], v[234:235] op_sel_hi:[1,0] neg_lo:[0,1] neg_hi:[0,1]
	v_pk_fma_f32 v[180:181], v[220:221], v[220:221], v[180:181]
	v_pk_add_f32 v[218:219], v[54:55], v[236:237] op_sel_hi:[1,0] neg_lo:[0,1] neg_hi:[0,1]
	v_pk_fma_f32 v[182:183], v[218:219], v[218:219], v[182:183]
	v_pk_add_f32 v[220:221], v[62:63], v[150:151] op_sel_hi:[1,0] neg_lo:[0,1] neg_hi:[0,1]
	v_pk_fma_f32 v[184:185], v[220:221], v[220:221], v[184:185]
	v_pk_add_f32 v[218:219], v[104:105], v[132:133] op_sel_hi:[1,0] neg_lo:[0,1] neg_hi:[0,1]
	v_pk_fma_f32 v[170:171], v[218:219], v[218:219], v[170:171]
	v_pk_add_f32 v[220:221], v[112:113], v[134:135] op_sel_hi:[1,0] neg_lo:[0,1] neg_hi:[0,1]
	v_pk_fma_f32 v[172:173], v[220:221], v[220:221], v[172:173]
	v_pk_add_f32 v[218:219], v[120:121], v[136:137] op_sel_hi:[1,0] neg_lo:[0,1] neg_hi:[0,1]
	v_pk_fma_f32 v[174:175], v[218:219], v[218:219], v[174:175]
	v_pk_add_f32 v[220:221], v[128:129], v[138:139] op_sel_hi:[1,0] neg_lo:[0,1] neg_hi:[0,1]
	v_pk_fma_f32 v[176:177], v[220:221], v[220:221], v[176:177]
	v_pk_add_f32 v[218:219], v[40:41], v[232:233] op_sel_hi:[1,0] neg_lo:[0,1] neg_hi:[0,1]
	v_pk_fma_f32 v[178:179], v[218:219], v[218:219], v[178:179]
	v_pk_add_f32 v[220:221], v[48:49], v[234:235] op_sel_hi:[1,0] neg_lo:[0,1] neg_hi:[0,1]
	v_pk_fma_f32 v[180:181], v[220:221], v[220:221], v[180:181]
	v_pk_add_f32 v[218:219], v[56:57], v[236:237] op_sel_hi:[1,0] neg_lo:[0,1] neg_hi:[0,1]
	v_pk_fma_f32 v[182:183], v[218:219], v[218:219], v[182:183]
	v_pk_add_f32 v[220:221], v[64:65], v[150:151] op_sel_hi:[1,0] neg_lo:[0,1] neg_hi:[0,1]
	v_pk_fma_f32 v[184:185], v[220:221], v[220:221], v[184:185]
	v_pk_add_f32 v[218:219], v[66:67], v[132:133] op_sel_hi:[1,0] neg_lo:[0,1] neg_hi:[0,1]
	v_pk_fma_f32 v[170:171], v[218:219], v[218:219], v[170:171]
	v_pk_add_f32 v[220:221], v[74:75], v[134:135] op_sel_hi:[1,0] neg_lo:[0,1] neg_hi:[0,1]
	v_pk_fma_f32 v[172:173], v[220:221], v[220:221], v[172:173]
	v_pk_add_f32 v[218:219], v[82:83], v[136:137] op_sel_hi:[1,0] neg_lo:[0,1] neg_hi:[0,1]
	v_pk_fma_f32 v[174:175], v[218:219], v[218:219], v[174:175]
	v_pk_add_f32 v[220:221], v[90:91], v[138:139] op_sel_hi:[1,0] neg_lo:[0,1] neg_hi:[0,1]
	v_pk_fma_f32 v[176:177], v[220:221], v[220:221], v[176:177]
	v_pk_add_f32 v[218:219], v[2:3], v[232:233] op_sel_hi:[1,0] neg_lo:[0,1] neg_hi:[0,1]
	v_pk_fma_f32 v[178:179], v[218:219], v[218:219], v[178:179]
	v_pk_add_f32 v[220:221], v[10:11], v[234:235] op_sel_hi:[1,0] neg_lo:[0,1] neg_hi:[0,1]
	v_pk_fma_f32 v[180:181], v[220:221], v[220:221], v[180:181]
	v_pk_add_f32 v[218:219], v[18:19], v[236:237] op_sel_hi:[1,0] neg_lo:[0,1] neg_hi:[0,1]
	v_pk_fma_f32 v[182:183], v[218:219], v[218:219], v[182:183]
	v_pk_add_f32 v[220:221], v[26:27], v[150:151] op_sel_hi:[1,0] neg_lo:[0,1] neg_hi:[0,1]
	v_pk_fma_f32 v[184:185], v[220:221], v[220:221], v[184:185]
	v_pk_add_f32 v[218:219], v[68:69], v[132:133] op_sel_hi:[1,0] neg_lo:[0,1] neg_hi:[0,1]
	v_pk_fma_f32 v[170:171], v[218:219], v[218:219], v[170:171]
	v_pk_add_f32 v[220:221], v[76:77], v[134:135] op_sel_hi:[1,0] neg_lo:[0,1] neg_hi:[0,1]
	v_pk_fma_f32 v[172:173], v[220:221], v[220:221], v[172:173]
	v_pk_add_f32 v[218:219], v[84:85], v[136:137] op_sel_hi:[1,0] neg_lo:[0,1] neg_hi:[0,1]
	v_pk_fma_f32 v[174:175], v[218:219], v[218:219], v[174:175]
	v_pk_add_f32 v[220:221], v[92:93], v[138:139] op_sel_hi:[1,0] neg_lo:[0,1] neg_hi:[0,1]
	v_pk_fma_f32 v[176:177], v[220:221], v[220:221], v[176:177]
	v_pk_add_f32 v[218:219], v[4:5], v[232:233] op_sel_hi:[1,0] neg_lo:[0,1] neg_hi:[0,1]
	v_pk_fma_f32 v[178:179], v[218:219], v[218:219], v[178:179]
	v_pk_add_f32 v[220:221], v[12:13], v[234:235] op_sel_hi:[1,0] neg_lo:[0,1] neg_hi:[0,1]
	v_pk_fma_f32 v[180:181], v[220:221], v[220:221], v[180:181]
	v_pk_add_f32 v[218:219], v[20:21], v[236:237] op_sel_hi:[1,0] neg_lo:[0,1] neg_hi:[0,1]
	v_pk_fma_f32 v[182:183], v[218:219], v[218:219], v[182:183]
	v_pk_add_f32 v[220:221], v[28:29], v[150:151] op_sel_hi:[1,0] neg_lo:[0,1] neg_hi:[0,1]
	v_pk_fma_f32 v[184:185], v[220:221], v[220:221], v[184:185]
	v_pk_add_f32 v[218:219], v[70:71], v[132:133] op_sel_hi:[1,0] neg_lo:[0,1] neg_hi:[0,1]
	v_pk_fma_f32 v[170:171], v[218:219], v[218:219], v[170:171]
	v_pk_add_f32 v[220:221], v[78:79], v[134:135] op_sel_hi:[1,0] neg_lo:[0,1] neg_hi:[0,1]
	v_pk_fma_f32 v[172:173], v[220:221], v[220:221], v[172:173]
	v_pk_add_f32 v[218:219], v[86:87], v[136:137] op_sel_hi:[1,0] neg_lo:[0,1] neg_hi:[0,1]
	v_pk_fma_f32 v[174:175], v[218:219], v[218:219], v[174:175]
	v_pk_add_f32 v[220:221], v[94:95], v[138:139] op_sel_hi:[1,0] neg_lo:[0,1] neg_hi:[0,1]
	v_pk_fma_f32 v[176:177], v[220:221], v[220:221], v[176:177]
	v_pk_add_f32 v[218:219], v[6:7], v[232:233] op_sel_hi:[1,0] neg_lo:[0,1] neg_hi:[0,1]
	v_pk_fma_f32 v[178:179], v[218:219], v[218:219], v[178:179]
	v_pk_add_f32 v[220:221], v[14:15], v[234:235] op_sel_hi:[1,0] neg_lo:[0,1] neg_hi:[0,1]
	v_pk_fma_f32 v[180:181], v[220:221], v[220:221], v[180:181]
	v_pk_add_f32 v[218:219], v[22:23], v[236:237] op_sel_hi:[1,0] neg_lo:[0,1] neg_hi:[0,1]
	v_pk_fma_f32 v[182:183], v[218:219], v[218:219], v[182:183]
	v_pk_add_f32 v[220:221], v[30:31], v[150:151] op_sel_hi:[1,0] neg_lo:[0,1] neg_hi:[0,1]
	v_pk_fma_f32 v[184:185], v[220:221], v[220:221], v[184:185]
	v_pk_add_f32 v[218:219], v[72:73], v[132:133] op_sel_hi:[1,0] neg_lo:[0,1] neg_hi:[0,1]
	v_pk_fma_f32 v[170:171], v[218:219], v[218:219], v[170:171]
	v_pk_add_f32 v[220:221], v[80:81], v[134:135] op_sel_hi:[1,0] neg_lo:[0,1] neg_hi:[0,1]
	v_pk_fma_f32 v[172:173], v[220:221], v[220:221], v[172:173]
	v_pk_add_f32 v[218:219], v[88:89], v[136:137] op_sel_hi:[1,0] neg_lo:[0,1] neg_hi:[0,1]
	v_pk_fma_f32 v[174:175], v[218:219], v[218:219], v[174:175]
	v_pk_add_f32 v[220:221], v[96:97], v[138:139] op_sel_hi:[1,0] neg_lo:[0,1] neg_hi:[0,1]
	v_pk_fma_f32 v[176:177], v[220:221], v[220:221], v[176:177]
	v_pk_add_f32 v[218:219], v[8:9], v[232:233] op_sel_hi:[1,0] neg_lo:[0,1] neg_hi:[0,1]
	v_pk_fma_f32 v[178:179], v[218:219], v[218:219], v[178:179]
	v_pk_add_f32 v[220:221], v[16:17], v[234:235] op_sel_hi:[1,0] neg_lo:[0,1] neg_hi:[0,1]
	v_pk_fma_f32 v[180:181], v[220:221], v[220:221], v[180:181]
	v_pk_add_f32 v[218:219], v[24:25], v[236:237] op_sel_hi:[1,0] neg_lo:[0,1] neg_hi:[0,1]
	v_pk_fma_f32 v[182:183], v[218:219], v[218:219], v[182:183]
	v_pk_add_f32 v[220:221], v[32:33], v[150:151] op_sel_hi:[1,0] neg_lo:[0,1] neg_hi:[0,1]
	v_pk_fma_f32 v[184:185], v[220:221], v[220:221], v[184:185]
	v_add_f32_e32 v133, v170, v171
	v_add_f32_e32 v135, v172, v173
	v_add_f32_e32 v137, v174, v175
	v_add_f32_e32 v139, v176, v177
	v_add_f32_e32 v233, v178, v179
	v_add_f32_e32 v235, v180, v181
	v_add_f32_e32 v237, v182, v183
	v_add_f32_e32 v151, v184, v185
	v_add_f32_dpp v133, v133, v133 quad_perm:[1,0,3,2] row_mask:0xf bank_mask:0xf
	v_add_f32_dpp v135, v135, v135 quad_perm:[1,0,3,2] row_mask:0xf bank_mask:0xf
	v_add_f32_dpp v137, v137, v137 quad_perm:[1,0,3,2] row_mask:0xf bank_mask:0xf
	v_add_f32_dpp v139, v139, v139 quad_perm:[1,0,3,2] row_mask:0xf bank_mask:0xf
	v_add_f32_dpp v233, v233, v233 quad_perm:[1,0,3,2] row_mask:0xf bank_mask:0xf
	v_add_f32_dpp v235, v235, v235 quad_perm:[1,0,3,2] row_mask:0xf bank_mask:0xf
	v_add_f32_dpp v237, v237, v237 quad_perm:[1,0,3,2] row_mask:0xf bank_mask:0xf
	v_add_f32_dpp v151, v151, v151 quad_perm:[1,0,3,2] row_mask:0xf bank_mask:0xf
	v_add_f32_dpp v133, v133, v133 quad_perm:[2,3,0,1] row_mask:0xf bank_mask:0xf
	v_add_f32_dpp v135, v135, v135 quad_perm:[2,3,0,1] row_mask:0xf bank_mask:0xf
	v_add_f32_dpp v137, v137, v137 quad_perm:[2,3,0,1] row_mask:0xf bank_mask:0xf
	v_add_f32_dpp v139, v139, v139 quad_perm:[2,3,0,1] row_mask:0xf bank_mask:0xf
	v_add_f32_dpp v233, v233, v233 quad_perm:[2,3,0,1] row_mask:0xf bank_mask:0xf
	v_add_f32_dpp v235, v235, v235 quad_perm:[2,3,0,1] row_mask:0xf bank_mask:0xf
	v_add_f32_dpp v237, v237, v237 quad_perm:[2,3,0,1] row_mask:0xf bank_mask:0xf
	v_add_f32_dpp v151, v151, v151 quad_perm:[2,3,0,1] row_mask:0xf bank_mask:0xf
	v_add_f32_dpp v133, v133, v133 row_half_mirror row_mask:0xf bank_mask:0xf
	v_add_f32_dpp v135, v135, v135 row_half_mirror row_mask:0xf bank_mask:0xf
	v_add_f32_dpp v137, v137, v137 row_half_mirror row_mask:0xf bank_mask:0xf
	v_add_f32_dpp v139, v139, v139 row_half_mirror row_mask:0xf bank_mask:0xf
	v_add_f32_dpp v233, v233, v233 row_half_mirror row_mask:0xf bank_mask:0xf
	v_add_f32_dpp v235, v235, v235 row_half_mirror row_mask:0xf bank_mask:0xf
	v_add_f32_dpp v237, v237, v237 row_half_mirror row_mask:0xf bank_mask:0xf
	v_add_f32_dpp v151, v151, v151 row_half_mirror row_mask:0xf bank_mask:0xf
	v_add_f32_dpp v133, v133, v133 row_mirror row_mask:0xf bank_mask:0xf
	v_add_f32_dpp v135, v135, v135 row_mirror row_mask:0xf bank_mask:0xf
	v_add_f32_dpp v137, v137, v137 row_mirror row_mask:0xf bank_mask:0xf
	v_add_f32_dpp v139, v139, v139 row_mirror row_mask:0xf bank_mask:0xf
	v_add_f32_dpp v233, v233, v233 row_mirror row_mask:0xf bank_mask:0xf
	v_add_f32_dpp v235, v235, v235 row_mirror row_mask:0xf bank_mask:0xf
	v_add_f32_dpp v237, v237, v237 row_mirror row_mask:0xf bank_mask:0xf
	v_add_f32_dpp v151, v151, v151 row_mirror row_mask:0xf bank_mask:0xf
	s_lshr_b32 s0, s73, 8
	s_lshl_b32 s0, s0, 13
	s_add_u32 s40, s62, 0xf100000
	s_addc_u32 s41, s63, 0
	s_add_u32 s40, s40, s0
	s_addc_u32 s41, s41, 0
	s_lshr_b32 s0, s46, 8
	s_lshl_b32 s0, s0, 11
	v_add_u32_e32 v224, s0, v227
	s_mov_b32 exec_lo, 0x10001
	s_mov_b32 exec_hi, 0x10001
	global_store_dwordx2 v224, v[132:133], s[40:41] offset:0 sc1
	global_store_dwordx2 v224, v[134:135], s[40:41] offset:256 sc1
	global_store_dwordx2 v224, v[136:137], s[40:41] offset:512 sc1
	global_store_dwordx2 v224, v[138:139], s[40:41] offset:768 sc1
	global_store_dwordx2 v224, v[232:233], s[40:41] offset:1024 sc1
	global_store_dwordx2 v224, v[234:235], s[40:41] offset:1280 sc1
	global_store_dwordx2 v224, v[236:237], s[40:41] offset:1536 sc1
	global_store_dwordx2 v224, v[150:151], s[40:41] offset:1792 sc1
	s_mov_b64 exec, -1
	s_waitcnt vmcnt(0)
	s_barrier
	v_readfirstlane_b32 s98, v0
	s_nop 3
	s_lshr_b32 s98, s98, 6
	s_cmp_lg_u32 s98, 0
	s_cbranch_scc1 .Lp9_wait_done
	s_lshr_b32 s99, s73, 8
	s_lshl_b32 s99, s99, 2
	s_add_u32 s44, s62, 0xf71a100
	s_addc_u32 s45, s63, 0
	s_add_u32 s44, s44, s99
	s_addc_u32 s45, s45, 0
	v_mov_b32_e32 v238, 0
	v_mov_b32_e32 v239, 1
	s_mov_b64 exec, 1
	global_atomic_add v238, v239, s[44:45]
	s_mov_b32 s99, 0
.Lp9_poll:
	global_load_dword v240, v238, s[44:45] sc1
	s_waitcnt vmcnt(0)
	v_readfirstlane_b32 s98, v240
	s_nop 3
	s_cmp_ge_u32 s98, 4
	s_cbranch_scc1 .Lp9_polled
	s_sleep 1
	s_add_i32 s99, s99, 1
	s_cmp_lt_u32 s99, 0x4000
	s_cbranch_scc1 .Lp9_poll

.Lp9_wait_done:
	s_barrier
	v_and_b32_e32 v246, 7, v0
	v_lshrrev_b32_e32 v247, 2, v246
	v_and_b32_e32 v246, 3, v246
	v_lshlrev_b32_e32 v247, 10, v247
	v_lshl_add_u32 v246, v246, 8, v247
	v_add_u32_e32 v246, v246, v227
	v_add_u32_e32 v247, 0x1000, v246
	global_load_dwordx2 v[238:239], v246, s[40:41] sc1
	global_load_dwordx2 v[240:241], v246, s[40:41] offset:2048 sc1
	global_load_dwordx2 v[242:243], v247, s[40:41] sc1
	global_load_dwordx2 v[244:245], v247, s[40:41] offset:2048 sc1
	v_mov_b32_e32 v248, 0x3727c5ac
	v_and_b32_e32 v249, 48, v0
	v_lshlrev_b32_e32 v249, 2, v249
	s_waitcnt vmcnt(0)
	v_add_f32_e32 v250, v238, v240
	v_add_f32_e32 v246, v242, v244
	v_add_f32_e32 v250, v250, v246
	v_mul_f32_e32 v250, 0x3e800000, v250
	v_sub_f32_e32 v238, v238, v250
	v_sub_f32_e32 v240, v240, v250
	v_sub_f32_e32 v242, v242, v250
	v_sub_f32_e32 v244, v244, v250
	v_mul_f32_e32 v246, v238, v238
	v_fmac_f32_e32 v246, v240, v240
	v_fmac_f32_e32 v246, v242, v242
	v_fmac_f32_e32 v246, v244, v244
	v_add_f32_e32 v239, v239, v241
	v_add_f32_e32 v243, v243, v245
	v_add_f32_e32 v239, v239, v243
	v_fmamk_f32 v246, v246, 0x43800000, v239
	v_fmamk_f32 v246, v246, 0x3a800000, v248
	v_rsq_f32_e32 v251, v246
	s_nop 0
	v_add_u32_e32 v240, 0, v249
	ds_bpermute_b32 v132, v240, v250
	ds_bpermute_b32 v133, v240, v251
	v_add_u32_e32 v241, 4, v249
	ds_bpermute_b32 v134, v241, v250
	ds_bpermute_b32 v135, v241, v251
	v_add_u32_e32 v240, 8, v249
	ds_bpermute_b32 v136, v240, v250
	ds_bpermute_b32 v137, v240, v251
	v_add_u32_e32 v241, 12, v249
	ds_bpermute_b32 v138, v241, v250
	ds_bpermute_b32 v139, v241, v251
	v_add_u32_e32 v240, 16, v249
	ds_bpermute_b32 v232, v240, v250
	ds_bpermute_b32 v233, v240, v251
	v_add_u32_e32 v241, 20, v249
	ds_bpermute_b32 v234, v241, v250
	ds_bpermute_b32 v235, v241, v251
	v_add_u32_e32 v240, 24, v249
	ds_bpermute_b32 v236, v240, v250
	ds_bpermute_b32 v237, v240, v251
	v_add_u32_e32 v241, 28, v249
	ds_bpermute_b32 v150, v241, v250
	ds_bpermute_b32 v151, v241, v251
	s_waitcnt lgkmcnt(0)
	s_lshr_b32 s0, s46, 8
	s_cmp_lg_u32 s0, 0
	s_cbranch_scc1 .Lp9_nostats
	s_mov_b32 exec_lo, 0x10001
	s_mov_b32 exec_hi, 0x10001
	global_store_dwordx2 v227, v[132:133], s[52:53] offset:0
	global_store_dwordx2 v227, v[134:135], s[52:53] offset:256
	global_store_dwordx2 v227, v[136:137], s[52:53] offset:512
	global_store_dwordx2 v227, v[138:139], s[52:53] offset:768
	global_store_dwordx2 v227, v[232:233], s[52:53] offset:1024
	global_store_dwordx2 v227, v[234:235], s[52:53] offset:1280
	global_store_dwordx2 v227, v[236:237], s[52:53] offset:1536
	global_store_dwordx2 v227, v[150:151], s[52:53] offset:1792
	s_mov_b64 exec, -1
.Lp9_nostats:
	s_mov_b32 s38, 0x0
	s_mov_b32 s39, 0
	v_lshl_add_u64 v[154:155], v[222:223], 0, s[38:39]
	v_pk_add_f32 v[98:99], v[98:99], v[132:133] op_sel_hi:[1,0] neg_lo:[0,1] neg_hi:[0,1]
	v_pk_mul_f32 v[98:99], v[98:99], v[132:133] op_sel:[0,1]
	v_pk_fma_f32 v[98:99], v[186:187], v[98:99], v[202:203]
	v_pk_add_f32 v[100:101], v[100:101], v[132:133] op_sel_hi:[1,0] neg_lo:[0,1] neg_hi:[0,1]
	v_pk_mul_f32 v[100:101], v[100:101], v[132:133] op_sel:[0,1]
	v_pk_fma_f32 v[100:101], v[188:189], v[100:101], v[204:205]
	v_pk_add_f32 v[102:103], v[102:103], v[132:133] op_sel_hi:[1,0] neg_lo:[0,1] neg_hi:[0,1]
	v_pk_mul_f32 v[102:103], v[102:103], v[132:133] op_sel:[0,1]
	v_pk_fma_f32 v[102:103], v[190:191], v[102:103], v[206:207]
	v_pk_add_f32 v[104:105], v[104:105], v[132:133] op_sel_hi:[1,0] neg_lo:[0,1] neg_hi:[0,1]
	v_pk_mul_f32 v[104:105], v[104:105], v[132:133] op_sel:[0,1]
	v_pk_fma_f32 v[104:105], v[192:193], v[104:105], v[208:209]
	v_cvt_pk_bf16_f32 v98, v98, v99
	v_cvt_pk_bf16_f32 v99, v100, v101
	v_cvt_pk_bf16_f32 v100, v102, v103
	v_cvt_pk_bf16_f32 v101, v104, v105
	global_store_dwordx4 v[154:155], v[98:101], off
	s_mov_b32 s38, 0x10000
	s_mov_b32 s39, 0
	v_lshl_add_u64 v[156:157], v[222:223], 0, s[38:39]
	v_pk_add_f32 v[106:107], v[106:107], v[134:135] op_sel_hi:[1,0] neg_lo:[0,1] neg_hi:[0,1]
	v_pk_mul_f32 v[106:107], v[106:107], v[134:135] op_sel:[0,1]
	v_pk_fma_f32 v[106:107], v[186:187], v[106:107], v[202:203]
	v_pk_add_f32 v[108:109], v[108:109], v[134:135] op_sel_hi:[1,0] neg_lo:[0,1] neg_hi:[0,1]
	v_pk_mul_f32 v[108:109], v[108:109], v[134:135] op_sel:[0,1]
	v_pk_fma_f32 v[108:109], v[188:189], v[108:109], v[204:205]
	v_pk_add_f32 v[110:111], v[110:111], v[134:135] op_sel_hi:[1,0] neg_lo:[0,1] neg_hi:[0,1]
	v_pk_mul_f32 v[110:111], v[110:111], v[134:135] op_sel:[0,1]
	v_pk_fma_f32 v[110:111], v[190:191], v[110:111], v[206:207]
	v_pk_add_f32 v[112:113], v[112:113], v[134:135] op_sel_hi:[1,0] neg_lo:[0,1] neg_hi:[0,1]
	v_pk_mul_f32 v[112:113], v[112:113], v[134:135] op_sel:[0,1]
	v_pk_fma_f32 v[112:113], v[192:193], v[112:113], v[208:209]
	v_cvt_pk_bf16_f32 v106, v106, v107
	v_cvt_pk_bf16_f32 v107, v108, v109
	v_cvt_pk_bf16_f32 v108, v110, v111
	v_cvt_pk_bf16_f32 v109, v112, v113
	global_store_dwordx4 v[156:157], v[106:109], off
	s_mov_b32 s38, 0x20000
	s_mov_b32 s39, 0
	v_lshl_add_u64 v[154:155], v[222:223], 0, s[38:39]
	v_pk_add_f32 v[114:115], v[114:115], v[136:137] op_sel_hi:[1,0] neg_lo:[0,1] neg_hi:[0,1]
	v_pk_mul_f32 v[114:115], v[114:115], v[136:137] op_sel:[0,1]
	v_pk_fma_f32 v[114:115], v[186:187], v[114:115], v[202:203]
	v_pk_add_f32 v[116:117], v[116:117], v[136:137] op_sel_hi:[1,0] neg_lo:[0,1] neg_hi:[0,1]
	v_pk_mul_f32 v[116:117], v[116:117], v[136:137] op_sel:[0,1]
	v_pk_fma_f32 v[116:117], v[188:189], v[116:117], v[204:205]
	v_pk_add_f32 v[118:119], v[118:119], v[136:137] op_sel_hi:[1,0] neg_lo:[0,1] neg_hi:[0,1]
	v_pk_mul_f32 v[118:119], v[118:119], v[136:137] op_sel:[0,1]
	v_pk_fma_f32 v[118:119], v[190:191], v[118:119], v[206:207]
	v_pk_add_f32 v[120:121], v[120:121], v[136:137] op_sel_hi:[1,0] neg_lo:[0,1] neg_hi:[0,1]
	v_pk_mul_f32 v[120:121], v[120:121], v[136:137] op_sel:[0,1]
	v_pk_fma_f32 v[120:121], v[192:193], v[120:121], v[208:209]
	v_cvt_pk_bf16_f32 v114, v114, v115
	v_cvt_pk_bf16_f32 v115, v116, v117
	v_cvt_pk_bf16_f32 v116, v118, v119
	v_cvt_pk_bf16_f32 v117, v120, v121
	global_store_dwordx4 v[154:155], v[114:117], off
	s_mov_b32 s38, 0x30000
	s_mov_b32 s39, 0
	v_lshl_add_u64 v[156:157], v[222:223], 0, s[38:39]
	v_pk_add_f32 v[122:123], v[122:123], v[138:139] op_sel_hi:[1,0] neg_lo:[0,1] neg_hi:[0,1]
	v_pk_mul_f32 v[122:123], v[122:123], v[138:139] op_sel:[0,1]
	v_pk_fma_f32 v[122:123], v[186:187], v[122:123], v[202:203]
	v_pk_add_f32 v[124:125], v[124:125], v[138:139] op_sel_hi:[1,0] neg_lo:[0,1] neg_hi:[0,1]
	v_pk_mul_f32 v[124:125], v[124:125], v[138:139] op_sel:[0,1]
	v_pk_fma_f32 v[124:125], v[188:189], v[124:125], v[204:205]
	v_pk_add_f32 v[126:127], v[126:127], v[138:139] op_sel_hi:[1,0] neg_lo:[0,1] neg_hi:[0,1]
	v_pk_mul_f32 v[126:127], v[126:127], v[138:139] op_sel:[0,1]
	v_pk_fma_f32 v[126:127], v[190:191], v[126:127], v[206:207]
	v_pk_add_f32 v[128:129], v[128:129], v[138:139] op_sel_hi:[1,0] neg_lo:[0,1] neg_hi:[0,1]
	v_pk_mul_f32 v[128:129], v[128:129], v[138:139] op_sel:[0,1]
	v_pk_fma_f32 v[128:129], v[192:193], v[128:129], v[208:209]
	v_cvt_pk_bf16_f32 v122, v122, v123
	v_cvt_pk_bf16_f32 v123, v124, v125
	v_cvt_pk_bf16_f32 v124, v126, v127
	v_cvt_pk_bf16_f32 v125, v128, v129
	global_store_dwordx4 v[156:157], v[122:125], off
	s_mov_b32 s38, 0x100
	s_mov_b32 s39, 0
	v_lshl_add_u64 v[154:155], v[222:223], 0, s[38:39]
	v_pk_add_f32 v[66:67], v[66:67], v[132:133] op_sel_hi:[1,0] neg_lo:[0,1] neg_hi:[0,1]
	v_pk_mul_f32 v[66:67], v[66:67], v[132:133] op_sel:[0,1]
	v_pk_fma_f32 v[66:67], v[194:195], v[66:67], v[210:211]
	v_pk_add_f32 v[68:69], v[68:69], v[132:133] op_sel_hi:[1,0] neg_lo:[0,1] neg_hi:[0,1]
	v_pk_mul_f32 v[68:69], v[68:69], v[132:133] op_sel:[0,1]
	v_pk_fma_f32 v[68:69], v[196:197], v[68:69], v[212:213]
	v_pk_add_f32 v[70:71], v[70:71], v[132:133] op_sel_hi:[1,0] neg_lo:[0,1] neg_hi:[0,1]
	v_pk_mul_f32 v[70:71], v[70:71], v[132:133] op_sel:[0,1]
	v_pk_fma_f32 v[70:71], v[198:199], v[70:71], v[214:215]
	v_pk_add_f32 v[72:73], v[72:73], v[132:133] op_sel_hi:[1,0] neg_lo:[0,1] neg_hi:[0,1]
	v_pk_mul_f32 v[72:73], v[72:73], v[132:133] op_sel:[0,1]
	v_pk_fma_f32 v[72:73], v[200:201], v[72:73], v[216:217]
	v_cvt_pk_bf16_f32 v66, v66, v67
	v_cvt_pk_bf16_f32 v67, v68, v69
	v_cvt_pk_bf16_f32 v68, v70, v71
	v_cvt_pk_bf16_f32 v69, v72, v73
	global_store_dwordx4 v[154:155], v[66:69], off
	s_mov_b32 s38, 0x10100
	s_mov_b32 s39, 0
	v_lshl_add_u64 v[156:157], v[222:223], 0, s[38:39]
	v_pk_add_f32 v[74:75], v[74:75], v[134:135] op_sel_hi:[1,0] neg_lo:[0,1] neg_hi:[0,1]
	v_pk_mul_f32 v[74:75], v[74:75], v[134:135] op_sel:[0,1]
	v_pk_fma_f32 v[74:75], v[194:195], v[74:75], v[210:211]
	v_pk_add_f32 v[76:77], v[76:77], v[134:135] op_sel_hi:[1,0] neg_lo:[0,1] neg_hi:[0,1]
	v_pk_mul_f32 v[76:77], v[76:77], v[134:135] op_sel:[0,1]
	v_pk_fma_f32 v[76:77], v[196:197], v[76:77], v[212:213]
	v_pk_add_f32 v[78:79], v[78:79], v[134:135] op_sel_hi:[1,0] neg_lo:[0,1] neg_hi:[0,1]
	v_pk_mul_f32 v[78:79], v[78:79], v[134:135] op_sel:[0,1]
	v_pk_fma_f32 v[78:79], v[198:199], v[78:79], v[214:215]
	v_pk_add_f32 v[80:81], v[80:81], v[134:135] op_sel_hi:[1,0] neg_lo:[0,1] neg_hi:[0,1]
	v_pk_mul_f32 v[80:81], v[80:81], v[134:135] op_sel:[0,1]
	v_pk_fma_f32 v[80:81], v[200:201], v[80:81], v[216:217]
	v_cvt_pk_bf16_f32 v74, v74, v75
	v_cvt_pk_bf16_f32 v75, v76, v77
	v_cvt_pk_bf16_f32 v76, v78, v79
	v_cvt_pk_bf16_f32 v77, v80, v81
	global_store_dwordx4 v[156:157], v[74:77], off
	s_mov_b32 s38, 0x20100
	s_mov_b32 s39, 0
	v_lshl_add_u64 v[154:155], v[222:223], 0, s[38:39]
	v_pk_add_f32 v[82:83], v[82:83], v[136:137] op_sel_hi:[1,0] neg_lo:[0,1] neg_hi:[0,1]
	v_pk_mul_f32 v[82:83], v[82:83], v[136:137] op_sel:[0,1]
	v_pk_fma_f32 v[82:83], v[194:195], v[82:83], v[210:211]
	v_pk_add_f32 v[84:85], v[84:85], v[136:137] op_sel_hi:[1,0] neg_lo:[0,1] neg_hi:[0,1]
	v_pk_mul_f32 v[84:85], v[84:85], v[136:137] op_sel:[0,1]
	v_pk_fma_f32 v[84:85], v[196:197], v[84:85], v[212:213]
	v_pk_add_f32 v[86:87], v[86:87], v[136:137] op_sel_hi:[1,0] neg_lo:[0,1] neg_hi:[0,1]
	v_pk_mul_f32 v[86:87], v[86:87], v[136:137] op_sel:[0,1]
	v_pk_fma_f32 v[86:87], v[198:199], v[86:87], v[214:215]
	v_pk_add_f32 v[88:89], v[88:89], v[136:137] op_sel_hi:[1,0] neg_lo:[0,1] neg_hi:[0,1]
	v_pk_mul_f32 v[88:89], v[88:89], v[136:137] op_sel:[0,1]
	v_pk_fma_f32 v[88:89], v[200:201], v[88:89], v[216:217]
	v_cvt_pk_bf16_f32 v82, v82, v83
	v_cvt_pk_bf16_f32 v83, v84, v85
	v_cvt_pk_bf16_f32 v84, v86, v87
	v_cvt_pk_bf16_f32 v85, v88, v89
	global_store_dwordx4 v[154:155], v[82:85], off
	s_mov_b32 s38, 0x30100
	s_mov_b32 s39, 0
	v_lshl_add_u64 v[156:157], v[222:223], 0, s[38:39]
	v_pk_add_f32 v[90:91], v[90:91], v[138:139] op_sel_hi:[1,0] neg_lo:[0,1] neg_hi:[0,1]
	v_pk_mul_f32 v[90:91], v[90:91], v[138:139] op_sel:[0,1]
	v_pk_fma_f32 v[90:91], v[194:195], v[90:91], v[210:211]
	v_pk_add_f32 v[92:93], v[92:93], v[138:139] op_sel_hi:[1,0] neg_lo:[0,1] neg_hi:[0,1]
	v_pk_mul_f32 v[92:93], v[92:93], v[138:139] op_sel:[0,1]
	v_pk_fma_f32 v[92:93], v[196:197], v[92:93], v[212:213]
	v_pk_add_f32 v[94:95], v[94:95], v[138:139] op_sel_hi:[1,0] neg_lo:[0,1] neg_hi:[0,1]
	v_pk_mul_f32 v[94:95], v[94:95], v[138:139] op_sel:[0,1]
	v_pk_fma_f32 v[94:95], v[198:199], v[94:95], v[214:215]
	v_pk_add_f32 v[96:97], v[96:97], v[138:139] op_sel_hi:[1,0] neg_lo:[0,1] neg_hi:[0,1]
	v_pk_mul_f32 v[96:97], v[96:97], v[138:139] op_sel:[0,1]
	v_pk_fma_f32 v[96:97], v[200:201], v[96:97], v[216:217]
	v_cvt_pk_bf16_f32 v90, v90, v91
	v_cvt_pk_bf16_f32 v91, v92, v93
	v_cvt_pk_bf16_f32 v92, v94, v95
	v_cvt_pk_bf16_f32 v93, v96, v97
	global_store_dwordx4 v[156:157], v[90:93], off
	s_mov_b32 s38, 0x40000
	s_mov_b32 s39, 0
	v_lshl_add_u64 v[154:155], v[222:223], 0, s[38:39]
	v_pk_add_f32 v[34:35], v[34:35], v[232:233] op_sel_hi:[1,0] neg_lo:[0,1] neg_hi:[0,1]
	v_pk_mul_f32 v[34:35], v[34:35], v[232:233] op_sel:[0,1]
	v_pk_fma_f32 v[34:35], v[186:187], v[34:35], v[202:203]
	v_pk_add_f32 v[36:37], v[36:37], v[232:233] op_sel_hi:[1,0] neg_lo:[0,1] neg_hi:[0,1]
	v_pk_mul_f32 v[36:37], v[36:37], v[232:233] op_sel:[0,1]
	v_pk_fma_f32 v[36:37], v[188:189], v[36:37], v[204:205]
	v_pk_add_f32 v[38:39], v[38:39], v[232:233] op_sel_hi:[1,0] neg_lo:[0,1] neg_hi:[0,1]
	v_pk_mul_f32 v[38:39], v[38:39], v[232:233] op_sel:[0,1]
	v_pk_fma_f32 v[38:39], v[190:191], v[38:39], v[206:207]
	v_pk_add_f32 v[40:41], v[40:41], v[232:233] op_sel_hi:[1,0] neg_lo:[0,1] neg_hi:[0,1]
	v_pk_mul_f32 v[40:41], v[40:41], v[232:233] op_sel:[0,1]
	v_pk_fma_f32 v[40:41], v[192:193], v[40:41], v[208:209]
	v_cvt_pk_bf16_f32 v34, v34, v35
	v_cvt_pk_bf16_f32 v35, v36, v37
	v_cvt_pk_bf16_f32 v36, v38, v39
	v_cvt_pk_bf16_f32 v37, v40, v41
	global_store_dwordx4 v[154:155], v[34:37], off
	s_mov_b32 s38, 0x50000
	s_mov_b32 s39, 0
	v_lshl_add_u64 v[156:157], v[222:223], 0, s[38:39]
	v_pk_add_f32 v[42:43], v[42:43], v[234:235] op_sel_hi:[1,0] neg_lo:[0,1] neg_hi:[0,1]
	v_pk_mul_f32 v[42:43], v[42:43], v[234:235] op_sel:[0,1]
	v_pk_fma_f32 v[42:43], v[186:187], v[42:43], v[202:203]
	v_pk_add_f32 v[44:45], v[44:45], v[234:235] op_sel_hi:[1,0] neg_lo:[0,1] neg_hi:[0,1]
	v_pk_mul_f32 v[44:45], v[44:45], v[234:235] op_sel:[0,1]
	v_pk_fma_f32 v[44:45], v[188:189], v[44:45], v[204:205]
	v_pk_add_f32 v[46:47], v[46:47], v[234:235] op_sel_hi:[1,0] neg_lo:[0,1] neg_hi:[0,1]
	v_pk_mul_f32 v[46:47], v[46:47], v[234:235] op_sel:[0,1]
	v_pk_fma_f32 v[46:47], v[190:191], v[46:47], v[206:207]
	v_pk_add_f32 v[48:49], v[48:49], v[234:235] op_sel_hi:[1,0] neg_lo:[0,1] neg_hi:[0,1]
	v_pk_mul_f32 v[48:49], v[48:49], v[234:235] op_sel:[0,1]
	v_pk_fma_f32 v[48:49], v[192:193], v[48:49], v[208:209]
	v_cvt_pk_bf16_f32 v42, v42, v43
	v_cvt_pk_bf16_f32 v43, v44, v45
	v_cvt_pk_bf16_f32 v44, v46, v47
	v_cvt_pk_bf16_f32 v45, v48, v49
	global_store_dwordx4 v[156:157], v[42:45], off
	s_mov_b32 s38, 0x60000
	s_mov_b32 s39, 0
	v_lshl_add_u64 v[154:155], v[222:223], 0, s[38:39]
	v_pk_add_f32 v[50:51], v[50:51], v[236:237] op_sel_hi:[1,0] neg_lo:[0,1] neg_hi:[0,1]
	v_pk_mul_f32 v[50:51], v[50:51], v[236:237] op_sel:[0,1]
	v_pk_fma_f32 v[50:51], v[186:187], v[50:51], v[202:203]
	v_pk_add_f32 v[52:53], v[52:53], v[236:237] op_sel_hi:[1,0] neg_lo:[0,1] neg_hi:[0,1]
	v_pk_mul_f32 v[52:53], v[52:53], v[236:237] op_sel:[0,1]
	v_pk_fma_f32 v[52:53], v[188:189], v[52:53], v[204:205]
	v_pk_add_f32 v[54:55], v[54:55], v[236:237] op_sel_hi:[1,0] neg_lo:[0,1] neg_hi:[0,1]
	v_pk_mul_f32 v[54:55], v[54:55], v[236:237] op_sel:[0,1]
	v_pk_fma_f32 v[54:55], v[190:191], v[54:55], v[206:207]
	v_pk_add_f32 v[56:57], v[56:57], v[236:237] op_sel_hi:[1,0] neg_lo:[0,1] neg_hi:[0,1]
	v_pk_mul_f32 v[56:57], v[56:57], v[236:237] op_sel:[0,1]
	v_pk_fma_f32 v[56:57], v[192:193], v[56:57], v[208:209]
	v_cvt_pk_bf16_f32 v50, v50, v51
	v_cvt_pk_bf16_f32 v51, v52, v53
	v_cvt_pk_bf16_f32 v52, v54, v55
	v_cvt_pk_bf16_f32 v53, v56, v57
	global_store_dwordx4 v[154:155], v[50:53], off
	s_mov_b32 s38, 0x70000
	s_mov_b32 s39, 0
	v_lshl_add_u64 v[156:157], v[222:223], 0, s[38:39]
	v_pk_add_f32 v[58:59], v[58:59], v[150:151] op_sel_hi:[1,0] neg_lo:[0,1] neg_hi:[0,1]
	v_pk_mul_f32 v[58:59], v[58:59], v[150:151] op_sel:[0,1]
	v_pk_fma_f32 v[58:59], v[186:187], v[58:59], v[202:203]
	v_pk_add_f32 v[60:61], v[60:61], v[150:151] op_sel_hi:[1,0] neg_lo:[0,1] neg_hi:[0,1]
	v_pk_mul_f32 v[60:61], v[60:61], v[150:151] op_sel:[0,1]
	v_pk_fma_f32 v[60:61], v[188:189], v[60:61], v[204:205]
	v_pk_add_f32 v[62:63], v[62:63], v[150:151] op_sel_hi:[1,0] neg_lo:[0,1] neg_hi:[0,1]
	v_pk_mul_f32 v[62:63], v[62:63], v[150:151] op_sel:[0,1]
	v_pk_fma_f32 v[62:63], v[190:191], v[62:63], v[206:207]
	v_pk_add_f32 v[64:65], v[64:65], v[150:151] op_sel_hi:[1,0] neg_lo:[0,1] neg_hi:[0,1]
	v_pk_mul_f32 v[64:65], v[64:65], v[150:151] op_sel:[0,1]
	v_pk_fma_f32 v[64:65], v[192:193], v[64:65], v[208:209]
	v_cvt_pk_bf16_f32 v58, v58, v59
	v_cvt_pk_bf16_f32 v59, v60, v61
	v_cvt_pk_bf16_f32 v60, v62, v63
	v_cvt_pk_bf16_f32 v61, v64, v65
	global_store_dwordx4 v[156:157], v[58:61], off
	s_mov_b32 s38, 0x40100
	s_mov_b32 s39, 0
	v_lshl_add_u64 v[154:155], v[222:223], 0, s[38:39]
	v_pk_add_f32 v[2:3], v[2:3], v[232:233] op_sel_hi:[1,0] neg_lo:[0,1] neg_hi:[0,1]
	v_pk_mul_f32 v[2:3], v[2:3], v[232:233] op_sel:[0,1]
	v_pk_fma_f32 v[2:3], v[194:195], v[2:3], v[210:211]
	v_pk_add_f32 v[4:5], v[4:5], v[232:233] op_sel_hi:[1,0] neg_lo:[0,1] neg_hi:[0,1]
	v_pk_mul_f32 v[4:5], v[4:5], v[232:233] op_sel:[0,1]
	v_pk_fma_f32 v[4:5], v[196:197], v[4:5], v[212:213]
	v_pk_add_f32 v[6:7], v[6:7], v[232:233] op_sel_hi:[1,0] neg_lo:[0,1] neg_hi:[0,1]
	v_pk_mul_f32 v[6:7], v[6:7], v[232:233] op_sel:[0,1]
	v_pk_fma_f32 v[6:7], v[198:199], v[6:7], v[214:215]
	v_pk_add_f32 v[8:9], v[8:9], v[232:233] op_sel_hi:[1,0] neg_lo:[0,1] neg_hi:[0,1]
	v_pk_mul_f32 v[8:9], v[8:9], v[232:233] op_sel:[0,1]
	v_pk_fma_f32 v[8:9], v[200:201], v[8:9], v[216:217]
	v_cvt_pk_bf16_f32 v2, v2, v3
	v_cvt_pk_bf16_f32 v3, v4, v5
	v_cvt_pk_bf16_f32 v4, v6, v7
	v_cvt_pk_bf16_f32 v5, v8, v9
	global_store_dwordx4 v[154:155], v[2:5], off
	s_mov_b32 s38, 0x50100
	s_mov_b32 s39, 0
	v_lshl_add_u64 v[156:157], v[222:223], 0, s[38:39]
	v_pk_add_f32 v[10:11], v[10:11], v[234:235] op_sel_hi:[1,0] neg_lo:[0,1] neg_hi:[0,1]
	v_pk_mul_f32 v[10:11], v[10:11], v[234:235] op_sel:[0,1]
	v_pk_fma_f32 v[10:11], v[194:195], v[10:11], v[210:211]
	v_pk_add_f32 v[12:13], v[12:13], v[234:235] op_sel_hi:[1,0] neg_lo:[0,1] neg_hi:[0,1]
	v_pk_mul_f32 v[12:13], v[12:13], v[234:235] op_sel:[0,1]
	v_pk_fma_f32 v[12:13], v[196:197], v[12:13], v[212:213]
	v_pk_add_f32 v[14:15], v[14:15], v[234:235] op_sel_hi:[1,0] neg_lo:[0,1] neg_hi:[0,1]
	v_pk_mul_f32 v[14:15], v[14:15], v[234:235] op_sel:[0,1]
	v_pk_fma_f32 v[14:15], v[198:199], v[14:15], v[214:215]
	v_pk_add_f32 v[16:17], v[16:17], v[234:235] op_sel_hi:[1,0] neg_lo:[0,1] neg_hi:[0,1]
	v_pk_mul_f32 v[16:17], v[16:17], v[234:235] op_sel:[0,1]
	v_pk_fma_f32 v[16:17], v[200:201], v[16:17], v[216:217]
	v_cvt_pk_bf16_f32 v10, v10, v11
	v_cvt_pk_bf16_f32 v11, v12, v13
	v_cvt_pk_bf16_f32 v12, v14, v15
	v_cvt_pk_bf16_f32 v13, v16, v17
	global_store_dwordx4 v[156:157], v[10:13], off
	s_mov_b32 s38, 0x60100
	s_mov_b32 s39, 0
	v_lshl_add_u64 v[154:155], v[222:223], 0, s[38:39]
	v_pk_add_f32 v[18:19], v[18:19], v[236:237] op_sel_hi:[1,0] neg_lo:[0,1] neg_hi:[0,1]
	v_pk_mul_f32 v[18:19], v[18:19], v[236:237] op_sel:[0,1]
	v_pk_fma_f32 v[18:19], v[194:195], v[18:19], v[210:211]
	v_pk_add_f32 v[20:21], v[20:21], v[236:237] op_sel_hi:[1,0] neg_lo:[0,1] neg_hi:[0,1]
	v_pk_mul_f32 v[20:21], v[20:21], v[236:237] op_sel:[0,1]
	v_pk_fma_f32 v[20:21], v[196:197], v[20:21], v[212:213]
	v_pk_add_f32 v[22:23], v[22:23], v[236:237] op_sel_hi:[1,0] neg_lo:[0,1] neg_hi:[0,1]
	v_pk_mul_f32 v[22:23], v[22:23], v[236:237] op_sel:[0,1]
	v_pk_fma_f32 v[22:23], v[198:199], v[22:23], v[214:215]
	v_pk_add_f32 v[24:25], v[24:25], v[236:237] op_sel_hi:[1,0] neg_lo:[0,1] neg_hi:[0,1]
	v_pk_mul_f32 v[24:25], v[24:25], v[236:237] op_sel:[0,1]
	v_pk_fma_f32 v[24:25], v[200:201], v[24:25], v[216:217]
	v_cvt_pk_bf16_f32 v18, v18, v19
	v_cvt_pk_bf16_f32 v19, v20, v21
	v_cvt_pk_bf16_f32 v20, v22, v23
	v_cvt_pk_bf16_f32 v21, v24, v25
	global_store_dwordx4 v[154:155], v[18:21], off
	s_mov_b32 s38, 0x70100
	s_mov_b32 s39, 0
	v_lshl_add_u64 v[156:157], v[222:223], 0, s[38:39]
	v_pk_add_f32 v[26:27], v[26:27], v[150:151] op_sel_hi:[1,0] neg_lo:[0,1] neg_hi:[0,1]
	v_pk_mul_f32 v[26:27], v[26:27], v[150:151] op_sel:[0,1]
	v_pk_fma_f32 v[26:27], v[194:195], v[26:27], v[210:211]
	v_pk_add_f32 v[28:29], v[28:29], v[150:151] op_sel_hi:[1,0] neg_lo:[0,1] neg_hi:[0,1]
	v_pk_mul_f32 v[28:29], v[28:29], v[150:151] op_sel:[0,1]
	v_pk_fma_f32 v[28:29], v[196:197], v[28:29], v[212:213]
	v_pk_add_f32 v[30:31], v[30:31], v[150:151] op_sel_hi:[1,0] neg_lo:[0,1] neg_hi:[0,1]
	v_pk_mul_f32 v[30:31], v[30:31], v[150:151] op_sel:[0,1]
	v_pk_fma_f32 v[30:31], v[198:199], v[30:31], v[214:215]
	v_pk_add_f32 v[32:33], v[32:33], v[150:151] op_sel_hi:[1,0] neg_lo:[0,1] neg_hi:[0,1]
	v_pk_mul_f32 v[32:33], v[32:33], v[150:151] op_sel:[0,1]
	v_pk_fma_f32 v[32:33], v[200:201], v[32:33], v[216:217]
	v_cvt_pk_bf16_f32 v26, v26, v27
	v_cvt_pk_bf16_f32 v27, v28, v29
	v_cvt_pk_bf16_f32 v28, v30, v31
	v_cvt_pk_bf16_f32 v29, v32, v33
	global_store_dwordx4 v[156:157], v[26:29], off
	s_mov_b64 s[46:47], 0
	s_waitcnt lgkmcnt(0)
	s_barrier
	s_branch .LBB0_1475

.LBB0_1476:
	s_waitcnt vmcnt(0)
	s_waitcnt vmcnt(0)
	s_barrier
	s_mov_b64 s[0:1], exec
	v_readlane_b32 s2, v253, 53
	v_readlane_b32 s3, v253, 54
	s_and_b64 s[2:3], s[0:1], s[2:3]
	s_mov_b64 exec, s[2:3]
	s_branch .LBB0_1528
	s_add_i32 s2, 0, 0x20000
	s_mov_b32 s12, s93
	v_mov_b32_e32 v1, s2
	s_waitcnt vmcnt(0) expcnt(0) lgkmcnt(0)
	ds_read_b32 v3, v1
	s_add_i32 s2, 0, 0x20004
	v_mov_b32_e32 v1, s2
	ds_read_b32 v2, v1
	s_waitcnt lgkmcnt(1)
	v_cmp_ne_u32_e32 vcc, 0, v3
	s_cbranch_vccnz .LBB0_1492
	s_mov_b32 s13, 1
	v_mov_b32_e32 v17, 0
	s_branch .LBB0_1480

.LBB0_1531:
.LBB0_1539:
	v_readlane_b32 s44, v254, 47
	v_readlane_b32 s38, v254, 42
	v_readlane_b32 s74, v254, 12
	v_readlane_b32 s42, v254, 14
	v_readlane_b32 s80, v254, 40
	v_readlane_b32 s86, v254, 38
	v_readlane_b32 s40, v254, 18
	v_readlane_b32 s45, v254, 48
	v_readlane_b32 s39, v254, 43
	v_readlane_b32 s75, v254, 13
	v_readlane_b32 s43, v254, 15
	v_readlane_b32 s81, v254, 41
	v_readlane_b32 s87, v254, 39
	v_readlane_b32 s41, v254, 19

.LBB0_1595:
	v_add_u32_e32 v2, s1, v168
	v_ashrrev_i32_e32 v3, 31, v2
	v_add_u32_e32 v4, 16, v2
	v_lshlrev_b64 v[2:3], 11, v[2:3]
	v_ashrrev_i32_e32 v5, 31, v4
	v_lshl_add_u64 v[2:3], v[156:157], 0, v[2:3]
	v_lshlrev_b64 v[6:7], 11, v[4:5]
	global_load_dwordx4 v[2:5], v[2:3], off
	v_lshl_add_u64 v[6:7], v[156:157], 0, v[6:7]
	global_load_dwordx4 v[114:117], v[6:7], off
	s_add_i32 s1, s1, 32
	s_cmpk_eq_i32 s1, 0x80
	s_waitcnt vmcnt(1)
	v_mfma_f32_32x32x16_bf16 v[176:191], v[2:5], v[130:133], 0
	v_mfma_f32_32x32x16_bf16 v[192:207], v[2:5], v[134:137], 0
	v_mfma_f32_32x32x16_bf16 v[208:223], v[2:5], v[138:141], 0
	v_mfma_f32_32x32x16_bf16 v[224:239], v[2:5], v[142:145], 0
	s_waitcnt vmcnt(0)
	v_mfma_f32_32x32x16_bf16 v[50:65], v[114:117], v[130:133], 0
	v_mfma_f32_32x32x16_bf16 v[66:81], v[114:117], v[134:137], 0
	v_mfma_f32_32x32x16_bf16 v[82:97], v[114:117], v[138:141], 0
	v_mfma_f32_32x32x16_bf16 v[98:113], v[114:117], v[142:145], 0
	s_nop 7
	v_fma_f32 v244, -v153, v35, v176
	v_fma_f32 v245, v153, v34, v192
	v_fma_f32 v246, -v155, v119, v208
	v_fma_f32 v247, v155, v118, v224
	v_fma_f32 v240, v152, v34, v244
	v_fma_f32 v241, v152, v35, v245
	v_fma_f32 v242, v154, v118, v246
	v_fma_f32 v243, v154, v119, v247
	v_fma_f32 v244, -v153, v241, v177
	v_fma_f32 v245, v153, v240, v193
	v_fma_f32 v246, -v155, v243, v209
	v_fma_f32 v247, v155, v242, v225
	v_fma_f32 v34, v152, v240, v244
	v_fma_f32 v35, v152, v241, v245
	v_fma_f32 v118, v154, v242, v246
	v_fma_f32 v119, v154, v243, v247
	v_fma_f32 v244, -v153, v35, v178
	v_fma_f32 v245, v153, v34, v194
	v_fma_f32 v246, -v155, v119, v210
	v_fma_f32 v247, v155, v118, v226
	v_fma_f32 v240, v152, v34, v244
	v_fma_f32 v241, v152, v35, v245
	v_fma_f32 v242, v154, v118, v246
	v_fma_f32 v243, v154, v119, v247
	v_fma_f32 v244, -v153, v241, v179
	v_fma_f32 v245, v153, v240, v195
	v_fma_f32 v246, -v155, v243, v211
	v_fma_f32 v247, v155, v242, v227
	v_fma_f32 v34, v152, v240, v244
	v_fma_f32 v35, v152, v241, v245
	v_fma_f32 v118, v154, v242, v246
	v_fma_f32 v119, v154, v243, v247
	v_fma_f32 v244, -v153, v35, v180
	v_fma_f32 v245, v153, v34, v196
	v_fma_f32 v246, -v155, v119, v212
	v_fma_f32 v247, v155, v118, v228
	v_fma_f32 v240, v152, v34, v244
	v_fma_f32 v241, v152, v35, v245
	v_fma_f32 v242, v154, v118, v246
	v_fma_f32 v243, v154, v119, v247
	v_fma_f32 v244, -v153, v241, v181
	v_fma_f32 v245, v153, v240, v197
	v_fma_f32 v246, -v155, v243, v213
	v_fma_f32 v247, v155, v242, v229
	v_fma_f32 v34, v152, v240, v244
	v_fma_f32 v35, v152, v241, v245
	v_fma_f32 v118, v154, v242, v246
	v_fma_f32 v119, v154, v243, v247
	v_fma_f32 v244, -v153, v35, v182
	v_fma_f32 v245, v153, v34, v198
	v_fma_f32 v246, -v155, v119, v214
	v_fma_f32 v247, v155, v118, v230
	v_fma_f32 v240, v152, v34, v244
	v_fma_f32 v241, v152, v35, v245
	v_fma_f32 v242, v154, v118, v246
	v_fma_f32 v243, v154, v119, v247
	v_fma_f32 v244, -v153, v241, v183
	v_fma_f32 v245, v153, v240, v199
	v_fma_f32 v246, -v155, v243, v215
	v_fma_f32 v247, v155, v242, v231
	v_fma_f32 v34, v152, v240, v244
	v_fma_f32 v35, v152, v241, v245
	v_fma_f32 v118, v154, v242, v246
	v_fma_f32 v119, v154, v243, v247
	v_fma_f32 v244, -v153, v35, v184
	v_fma_f32 v245, v153, v34, v200
	v_fma_f32 v246, -v155, v119, v216
	v_fma_f32 v247, v155, v118, v232
	v_fma_f32 v240, v152, v34, v244
	v_fma_f32 v241, v152, v35, v245
	v_fma_f32 v242, v154, v118, v246
	v_fma_f32 v243, v154, v119, v247
	v_fma_f32 v244, -v153, v241, v185
	v_fma_f32 v245, v153, v240, v201
	v_fma_f32 v246, -v155, v243, v217
	v_fma_f32 v247, v155, v242, v233
	v_fma_f32 v34, v152, v240, v244
	v_fma_f32 v35, v152, v241, v245
	v_fma_f32 v118, v154, v242, v246
	v_fma_f32 v119, v154, v243, v247
	v_fma_f32 v244, -v153, v35, v186
	v_fma_f32 v245, v153, v34, v202
	v_fma_f32 v246, -v155, v119, v218
	v_fma_f32 v247, v155, v118, v234
	v_fma_f32 v240, v152, v34, v244
	v_fma_f32 v241, v152, v35, v245
	v_fma_f32 v242, v154, v118, v246
	v_fma_f32 v243, v154, v119, v247
	v_fma_f32 v244, -v153, v241, v187
	v_fma_f32 v245, v153, v240, v203
	v_fma_f32 v246, -v155, v243, v219
	v_fma_f32 v247, v155, v242, v235
	v_fma_f32 v34, v152, v240, v244
	v_fma_f32 v35, v152, v241, v245
	v_fma_f32 v118, v154, v242, v246
	v_fma_f32 v119, v154, v243, v247
	v_fma_f32 v244, -v153, v35, v188
	v_fma_f32 v245, v153, v34, v204
	v_fma_f32 v246, -v155, v119, v220
	v_fma_f32 v247, v155, v118, v236
	v_fma_f32 v240, v152, v34, v244
	v_fma_f32 v241, v152, v35, v245
	v_fma_f32 v242, v154, v118, v246
	v_fma_f32 v243, v154, v119, v247
	v_fma_f32 v244, -v153, v241, v189
	v_fma_f32 v245, v153, v240, v205
	v_fma_f32 v246, -v155, v243, v221
	v_fma_f32 v247, v155, v242, v237
	v_fma_f32 v34, v152, v240, v244
	v_fma_f32 v35, v152, v241, v245
	v_fma_f32 v118, v154, v242, v246
	v_fma_f32 v119, v154, v243, v247
	v_fma_f32 v244, -v153, v35, v190
	v_fma_f32 v245, v153, v34, v206
	v_fma_f32 v246, -v155, v119, v222
	v_fma_f32 v247, v155, v118, v238
	v_fma_f32 v240, v152, v34, v244
	v_fma_f32 v241, v152, v35, v245
	v_fma_f32 v242, v154, v118, v246
	v_fma_f32 v243, v154, v119, v247
	v_fma_f32 v244, -v153, v241, v191
	v_fma_f32 v245, v153, v240, v207
	v_fma_f32 v246, -v155, v243, v223
	v_fma_f32 v247, v155, v242, v239
	v_fma_f32 v34, v152, v240, v244
	v_fma_f32 v35, v152, v241, v245
	v_fma_f32 v118, v154, v242, v246
	v_fma_f32 v119, v154, v243, v247
	v_fma_f32 v244, -v153, v35, v50
	v_fma_f32 v245, v153, v34, v66
	v_fma_f32 v246, -v155, v119, v82
	v_fma_f32 v247, v155, v118, v98
	v_fma_f32 v240, v152, v34, v244
	v_fma_f32 v241, v152, v35, v245
	v_fma_f32 v242, v154, v118, v246
	v_fma_f32 v243, v154, v119, v247
	v_fma_f32 v244, -v153, v241, v51
	v_fma_f32 v245, v153, v240, v67
	v_fma_f32 v246, -v155, v243, v83
	v_fma_f32 v247, v155, v242, v99
	v_fma_f32 v34, v152, v240, v244
	v_fma_f32 v35, v152, v241, v245
	v_fma_f32 v118, v154, v242, v246
	v_fma_f32 v119, v154, v243, v247
	v_fma_f32 v244, -v153, v35, v52
	v_fma_f32 v245, v153, v34, v68
	v_fma_f32 v246, -v155, v119, v84
	v_fma_f32 v247, v155, v118, v100
	v_fma_f32 v240, v152, v34, v244
	v_fma_f32 v241, v152, v35, v245
	v_fma_f32 v242, v154, v118, v246
	v_fma_f32 v243, v154, v119, v247
	v_fma_f32 v244, -v153, v241, v53
	v_fma_f32 v245, v153, v240, v69
	v_fma_f32 v246, -v155, v243, v85
	v_fma_f32 v247, v155, v242, v101
	v_fma_f32 v34, v152, v240, v244
	v_fma_f32 v35, v152, v241, v245
	v_fma_f32 v118, v154, v242, v246
	v_fma_f32 v119, v154, v243, v247
	v_fma_f32 v244, -v153, v35, v54
	v_fma_f32 v245, v153, v34, v70
	v_fma_f32 v246, -v155, v119, v86
	v_fma_f32 v247, v155, v118, v102
	v_fma_f32 v240, v152, v34, v244
	v_fma_f32 v241, v152, v35, v245
	v_fma_f32 v242, v154, v118, v246
	v_fma_f32 v243, v154, v119, v247
	v_fma_f32 v244, -v153, v241, v55
	v_fma_f32 v245, v153, v240, v71
	v_fma_f32 v246, -v155, v243, v87
	v_fma_f32 v247, v155, v242, v103
	v_fma_f32 v34, v152, v240, v244
	v_fma_f32 v35, v152, v241, v245
	v_fma_f32 v118, v154, v242, v246
	v_fma_f32 v119, v154, v243, v247
	v_fma_f32 v244, -v153, v35, v56
	v_fma_f32 v245, v153, v34, v72
	v_fma_f32 v246, -v155, v119, v88
	v_fma_f32 v247, v155, v118, v104
	v_fma_f32 v240, v152, v34, v244
	v_fma_f32 v241, v152, v35, v245
	v_fma_f32 v242, v154, v118, v246
	v_fma_f32 v243, v154, v119, v247
	v_fma_f32 v244, -v153, v241, v57
	v_fma_f32 v245, v153, v240, v73
	v_fma_f32 v246, -v155, v243, v89
	v_fma_f32 v247, v155, v242, v105
	v_fma_f32 v34, v152, v240, v244
	v_fma_f32 v35, v152, v241, v245
	v_fma_f32 v118, v154, v242, v246
	v_fma_f32 v119, v154, v243, v247
	v_fma_f32 v244, -v153, v35, v58
	v_fma_f32 v245, v153, v34, v74
	v_fma_f32 v246, -v155, v119, v90
	v_fma_f32 v247, v155, v118, v106
	v_fma_f32 v240, v152, v34, v244
	v_fma_f32 v241, v152, v35, v245
	v_fma_f32 v242, v154, v118, v246
	v_fma_f32 v243, v154, v119, v247
	v_fma_f32 v244, -v153, v241, v59
	v_fma_f32 v245, v153, v240, v75
	v_fma_f32 v246, -v155, v243, v91
	v_fma_f32 v247, v155, v242, v107
	v_fma_f32 v34, v152, v240, v244
	v_fma_f32 v35, v152, v241, v245
	v_fma_f32 v118, v154, v242, v246
	v_fma_f32 v119, v154, v243, v247
	v_fma_f32 v244, -v153, v35, v60
	v_fma_f32 v245, v153, v34, v76
	v_fma_f32 v246, -v155, v119, v92
	v_fma_f32 v247, v155, v118, v108
	v_fma_f32 v240, v152, v34, v244
	v_fma_f32 v241, v152, v35, v245
	v_fma_f32 v242, v154, v118, v246
	v_fma_f32 v243, v154, v119, v247
	v_fma_f32 v244, -v153, v241, v61
	v_fma_f32 v245, v153, v240, v77
	v_fma_f32 v246, -v155, v243, v93
	v_fma_f32 v247, v155, v242, v109
	v_fma_f32 v34, v152, v240, v244
	v_fma_f32 v35, v152, v241, v245
	v_fma_f32 v118, v154, v242, v246
	v_fma_f32 v119, v154, v243, v247
	v_fma_f32 v244, -v153, v35, v62
	v_fma_f32 v245, v153, v34, v78
	v_fma_f32 v246, -v155, v119, v94
	v_fma_f32 v247, v155, v118, v110
	v_fma_f32 v240, v152, v34, v244
	v_fma_f32 v241, v152, v35, v245
	v_fma_f32 v242, v154, v118, v246
	v_fma_f32 v243, v154, v119, v247
	v_fma_f32 v244, -v153, v241, v63
	v_fma_f32 v245, v153, v240, v79
	v_fma_f32 v246, -v155, v243, v95
	v_fma_f32 v247, v155, v242, v111
	v_fma_f32 v34, v152, v240, v244
	v_fma_f32 v35, v152, v241, v245
	v_fma_f32 v118, v154, v242, v246
	v_fma_f32 v119, v154, v243, v247
	v_fma_f32 v244, -v153, v35, v64
	v_fma_f32 v245, v153, v34, v80
	v_fma_f32 v246, -v155, v119, v96
	v_fma_f32 v247, v155, v118, v112
	v_fma_f32 v240, v152, v34, v244
	v_fma_f32 v241, v152, v35, v245
	v_fma_f32 v242, v154, v118, v246
	v_fma_f32 v243, v154, v119, v247
	v_fma_f32 v244, -v153, v241, v65
	v_fma_f32 v245, v153, v240, v81
	v_fma_f32 v246, -v155, v243, v97
	v_fma_f32 v247, v155, v242, v113
	v_fma_f32 v34, v152, v240, v244
	v_fma_f32 v35, v152, v241, v245
	v_fma_f32 v118, v154, v242, v246
	v_fma_f32 v119, v154, v243, v247
	s_cbranch_scc0 .LBB0_1595
	s_nop 0
	s_nop 0
	s_nop 0
	s_nop 0
	s_nop 0
	v_lshlrev_b32_e32 v2, 7, v167
	v_or3_b32 v2, v2, v163, v166
	v_ashrrev_i32_e32 v3, 31, v2
	v_lshlrev_b64 v[2:3], 9, v[2:3]
	s_add_i32 s0, s0, s96
	v_lshl_add_u64 v[2:3], v[150:151], 0, v[2:3]
	s_cmpk_gt_i32 s0, 0x1ff
	global_store_dwordx2 v[2:3], v[34:35], off
	global_store_dwordx2 v[2:3], v[118:119], off offset:256
	s_cbranch_scc0 .LBB0_1594
